# scan_pair chunk scan re-rolled into loops (was fully unrolled straight-line code, instruction-fetch bound); same f32 math
# speedup vs baseline: 1.0181x; 1.0025x over previous
; #define LAS __attribute__((address_space(3)))
; __device__ __forceinline__ void scan_pair(Frame& F, const int g, const int b, unsigned long long& pt0, unsigned long long& pt1) {
;     ...
;     const f32x4 za = *(const f32x4*)((const float*)(F.ws + WS_ZA) + ((size_t)(r * NG + g) * 64 + n) * 4);
;     const float aTr = za[2], aTi = za[3];
;     float hr, hi;
;     LAS unsigned char* uct = F.lds + 16384;
;     LAS float* sctx = (LAS float*)(F.lds + 16384 + 8 * 1040);
;     {   const int tt = (F.wave * 64 + n) >> 1, hf = n & 1;
;         f32x4 a0 = {0.f, 0.f, 0.f, 0.f}, a1 = a0;
; #pragma unroll
;         for (int ks = 0; ks < 4; ++ks) { const f32x4* rp = (const f32x4*)((const float*)(F.ws + WS_UCS) + ((((size_t)g * 4 + ks) * RC + b * CTXL + tt) * 16) + hf * 8); a0 += rp[0]; a1 += rp[1]; }
;         u32x4 w; w.x = pk2(a0[0], a0[1]); w.y = pk2(a0[2], a0[3]); w.z = pk2(a1[0], a1[1]); w.w = pk2(a1[2], a1[3]);
;         *(LAS u32x4*)(uct + (tt >> 5) * 1040 + ((tt & 31) * 16 + hf * 8) * 2) = w; }
;     __syncthreads();
;     {   const int kg = n >> 4, cl = n & 15;
;         const char* m2 = (const char*)(F.ws + WS_M2 + (size_t)g * MiB);
; #pragma unroll
;         for (int jb = 0; jb < 2; ++jb) { const int j = (F.wave * 2 + jb) * 16 + cl;
;             bf16x8 bm[16];
; #pragma unroll
;             for (int kt = 0; kt < 16; ++kt) bm[kt] = *(const bf16x8*)(m2 + ((size_t)((kt * 32 + kg * 8) >> 6) * 256 + j) * 128 + ((kt * 32 + kg * 8) & 63) * 2);
;             f32x4 d = {0.f, 0.f, 0.f, 0.f};
; #pragma unroll
;             for (int kt = 0; kt < 16; ++kt) { const bf16x8 au = *(const LAS bf16x8*)(uct + (cl & 7) * 1040 + (kt * 32 + kg * 8) * 2);
;                 d = __builtin_amdgcn_mfma_f32_16x16x32_bf16(au, bm[kt], d, 0, 0, 0); }
.LBB0_545:
	v_readlane_b32 s10, v252, 0
	s_add_i32 s4, s10, s60
	s_ashr_i32 s5, s4, 31
	s_lshl_b64 s[4:5], s[4:5], 10
	v_readlane_b32 s6, v253, 53
	v_mov_b32_e32 v74, v209
	s_add_u32 s4, s6, s4
	v_readlane_b32 s6, v253, 54
	s_waitcnt vmcnt(0)
	s_barrier
	s_waitcnt vmcnt(0)
	s_waitcnt vmcnt(0)
	s_barrier
	s_addc_u32 s5, s6, s5
	v_ashrrev_i32_e32 v75, 31, v74
	v_lshl_add_u64 v[2:3], v[74:75], 4, s[4:5]
	v_readlane_b32 s4, v253, 55
	global_load_dwordx4 v[246:249], v[2:3], off
	s_lshl_b32 s6, s2, 8
	v_add_u32_e32 v24, s4, v74
	v_ashrrev_i32_e32 v2, 1, v24
	s_lshl_b64 s[4:5], s[60:61], 11
	v_ashrrev_i32_e32 v3, 31, v2
	s_or_b32 s4, s4, s6
	v_and_b32_e32 v25, 1, v74
	v_lshl_add_u64 v[6:7], s[4:5], 0, v[2:3]
	v_readlane_b32 s4, v253, 56
	v_lshlrev_b32_e32 v130, 5, v25
	v_readlane_b32 s5, v253, 57
	v_lshlrev_b64 v[6:7], 6, v[6:7]
	v_ashrrev_i32_e32 v3, 6, v24
	v_lshl_add_u64 v[8:9], s[4:5], 0, v[130:131]
	v_lshl_add_u64 v[14:15], v[8:9], 0, v[6:7]
	v_lshl_add_u64 v[202:203], v[14:15], 0, s[8:9]
	s_mov_b64 s[4:5], 0x10000
	v_lshl_add_u64 v[204:205], v[14:15], 0, s[4:5]
	s_mov_b64 s[4:5], 0x18000
	v_lshl_add_u64 v[206:207], v[14:15], 0, s[4:5]
	global_load_dwordx4 v[170:173], v[14:15], off
	global_load_dwordx4 v[174:177], v[14:15], off offset:16
	global_load_dwordx4 v[178:181], v[202:203], off
	global_load_dwordx4 v[182:185], v[202:203], off offset:16
	global_load_dwordx4 v[186:189], v[204:205], off
	global_load_dwordx4 v[190:193], v[204:205], off offset:16
	global_load_dwordx4 v[194:197], v[206:207], off
	global_load_dwordx4 v[198:201], v[206:207], off offset:16
	v_lshlrev_b32_e32 v2, 5, v2
	v_and_b32_e32 v2, 0x3e0, v2
	v_and_b32_e32 v169, 15, v74
	v_ashrrev_i32_e32 v168, 4, v74
	v_and_b32_e32 v130, 0x70, v74
	v_mov_b32_e32 v123, v131
	v_mov_b32_e32 v83, v131
	v_mov_b32_e32 v89, v131
	v_mov_b32_e32 v95, v131
	v_mov_b32_e32 v101, v131
	v_mov_b32_e32 v107, v131
	v_mov_b32_e32 v121, v131
	v_mov_b32_e32 v113, v131
	v_readlane_b32 s11, v252, 1
	s_movk_i32 s4, 0x410
	v_mul_lo_u32 v3, v3, s4
	v_add_u32_e32 v3, 0, v3
	v_cmp_gt_i32_e32 vcc, 2, v168
	s_waitcnt vmcnt(6)
	v_pk_add_f32 v[22:23], v[174:175], 0 op_sel_hi:[1,0]
	v_pk_add_f32 v[18:19], v[170:171], 0 op_sel_hi:[1,0]
	v_pk_add_f32 v[16:17], v[172:173], 0 op_sel_hi:[1,0]
	v_pk_add_f32 v[20:21], v[176:177], 0 op_sel_hi:[1,0]
	s_waitcnt vmcnt(4)
	v_pk_add_f32 v[18:19], v[18:19], v[178:179]
	v_pk_add_f32 v[22:23], v[22:23], v[182:183]
	v_pk_add_f32 v[16:17], v[16:17], v[180:181]
	v_pk_add_f32 v[20:21], v[20:21], v[184:185]
	s_waitcnt vmcnt(2)
	v_pk_add_f32 v[18:19], v[18:19], v[186:187]
	v_pk_add_f32 v[22:23], v[22:23], v[190:191]
	v_pk_add_f32 v[16:17], v[16:17], v[188:189]
	v_pk_add_f32 v[20:21], v[20:21], v[192:193]
	s_waitcnt vmcnt(0)
	v_pk_add_f32 v[8:9], v[16:17], v[196:197]
	v_pk_add_f32 v[6:7], v[18:19], v[194:195]
	v_pk_add_f32 v[10:11], v[22:23], v[198:199]
	v_pk_add_f32 v[12:13], v[20:21], v[200:201]
	v_cvt_pk_bf16_f32 v6, v6, v7
	v_cvt_pk_bf16_f32 v7, v8, v9
	v_cvt_pk_bf16_f32 v8, v10, v11
	v_lshlrev_b32_e32 v10, 4, v25
	v_cvt_pk_bf16_f32 v9, v12, v13
	v_add3_u32 v2, v3, v2, v10
	v_and_b32_e32 v3, -16, v74
	ds_write_b128 v2, v[6:9] offset:16384
	v_and_b32_e32 v2, 7, v74
	v_add_u32_e32 v124, 0, v3
	v_mad_u32_u24 v8, v2, s4, v124
	v_readlane_b32 s4, v253, 58
	v_mov_b32_e32 v3, v131
	v_ashrrev_i32_e32 v10, 7, v74
	v_or_b32_e32 v2, s4, v169
	v_lshlrev_b64 v[6:7], 7, v[2:3]
	v_ashrrev_i32_e32 v11, 31, v10
	v_lshlrev_b32_e32 v9, 3, v168
	v_lshl_add_u64 v[6:7], s[82:83], 0, v[6:7]
	v_lshlrev_b64 v[76:77], 15, v[10:11]
	v_lshl_add_u64 v[10:11], v[6:7], 0, v[76:77]
	v_add_u32_e32 v3, 32, v9
	v_lshl_add_u64 v[10:11], v[10:11], 0, v[130:131]
	v_ashrrev_i32_e32 v14, 6, v3
	s_waitcnt lgkmcnt(0)
	s_barrier
	global_load_dwordx4 v[10:13], v[10:11], off
	v_ashrrev_i32_e32 v15, 31, v14
	v_lshlrev_b64 v[118:119], 15, v[14:15]
	v_lshlrev_b32_e32 v3, 1, v3
	v_lshl_add_u64 v[14:15], v[6:7], 0, v[118:119]
	v_and_b32_e32 v122, 0x70, v3
	v_add_u32_e32 v3, 64, v9
	v_lshl_add_u64 v[14:15], v[14:15], 0, v[122:123]
	v_ashrrev_i32_e32 v18, 6, v3
	global_load_dwordx4 v[14:17], v[14:15], off
	v_ashrrev_i32_e32 v19, 31, v18
	v_lshlrev_b64 v[78:79], 15, v[18:19]
	v_add_u32_e32 v3, 0x60, v9
	v_lshl_add_u64 v[18:19], v[6:7], 0, v[78:79]
	v_ashrrev_i32_e32 v22, 6, v3
	v_lshl_add_u64 v[18:19], v[18:19], 0, v[130:131]
	v_ashrrev_i32_e32 v23, 31, v22
	global_load_dwordx4 v[18:21], v[18:19], off
	v_lshlrev_b64 v[80:81], 15, v[22:23]
	v_lshlrev_b32_e32 v3, 1, v3
	v_lshl_add_u64 v[22:23], v[6:7], 0, v[80:81]
	v_and_b32_e32 v82, 0x70, v3
	v_lshl_add_u64 v[22:23], v[22:23], 0, v[82:83]
	v_add_u32_e32 v3, 0x80, v9
	global_load_dwordx4 v[34:37], v[22:23], off
	v_ashrrev_i32_e32 v22, 6, v3
	v_ashrrev_i32_e32 v23, 31, v22
	v_lshlrev_b64 v[84:85], 15, v[22:23]
	v_lshl_add_u64 v[22:23], v[6:7], 0, v[84:85]
	v_lshl_add_u64 v[22:23], v[22:23], 0, v[130:131]
	global_load_dwordx4 v[42:45], v[22:23], off
	v_add_u32_e32 v3, 0xa0, v9
	v_ashrrev_i32_e32 v22, 6, v3
	v_ashrrev_i32_e32 v23, 31, v22
	v_lshlrev_b64 v[86:87], 15, v[22:23]
	v_lshlrev_b32_e32 v3, 1, v3
	v_lshl_add_u64 v[22:23], v[6:7], 0, v[86:87]
	v_and_b32_e32 v88, 0x70, v3
	v_lshl_add_u64 v[22:23], v[22:23], 0, v[88:89]
	v_add_u32_e32 v3, 0xc0, v9
	global_load_dwordx4 v[46:49], v[22:23], off
	v_ashrrev_i32_e32 v22, 6, v3
	v_ashrrev_i32_e32 v23, 31, v22
	v_lshlrev_b64 v[90:91], 15, v[22:23]
	v_lshl_add_u64 v[22:23], v[6:7], 0, v[90:91]
	v_lshl_add_u64 v[22:23], v[22:23], 0, v[130:131]
	v_add_u32_e32 v3, 0xe0, v9
	global_load_dwordx4 v[50:53], v[22:23], off
	v_ashrrev_i32_e32 v22, 6, v3
	v_ashrrev_i32_e32 v23, 31, v22
	v_lshlrev_b64 v[92:93], 15, v[22:23]
	v_lshlrev_b32_e32 v3, 1, v3
; #define LAS __attribute__((address_space(3)))
; __device__ __forceinline__ void scan_pair(Frame& F, const int g, const int b, unsigned long long& pt0, unsigned long long& pt1) {
;     ...
;     {   const int kg = n >> 4, cl = n & 15;
;         const char* m2 = (const char*)(F.ws + WS_M2 + (size_t)g * MiB);
; #pragma unroll
;         for (int jb = 0; jb < 2; ++jb) { const int j = (F.wave * 2 + jb) * 16 + cl;
;             bf16x8 bm[16];
; #pragma unroll
;             for (int kt = 0; kt < 16; ++kt) bm[kt] = *(const bf16x8*)(m2 + ((size_t)((kt * 32 + kg * 8) >> 6) * 256 + j) * 128 + ((kt * 32 + kg * 8) & 63) * 2);
;             f32x4 d = {0.f, 0.f, 0.f, 0.f};
; #pragma unroll
;             for (int kt = 0; kt < 16; ++kt) { const bf16x8 au = *(const LAS bf16x8*)(uct + (cl & 7) * 1040 + (kt * 32 + kg * 8) * 2);
;                 d = __builtin_amdgcn_mfma_f32_16x16x32_bf16(au, bm[kt], d, 0, 0, 0); }
;             if (kg < 2) *(LAS f32x4*)(sctx + j * 8 + 4 * kg) = d; } }
	v_lshl_add_u64 v[22:23], v[6:7], 0, v[92:93]
	v_and_b32_e32 v94, 0x70, v3
	v_lshl_add_u64 v[22:23], v[22:23], 0, v[94:95]
	v_add_u32_e32 v3, 0x100, v9
	global_load_dwordx4 v[58:61], v[22:23], off
	v_ashrrev_i32_e32 v22, 6, v3
	v_ashrrev_i32_e32 v23, 31, v22
	v_lshlrev_b64 v[96:97], 15, v[22:23]
	v_lshl_add_u64 v[22:23], v[6:7], 0, v[96:97]
	v_lshl_add_u64 v[22:23], v[22:23], 0, v[130:131]
	v_add_u32_e32 v3, 0x120, v9
	global_load_dwordx4 v[70:73], v[22:23], off
	v_ashrrev_i32_e32 v22, 6, v3
	v_ashrrev_i32_e32 v23, 31, v22
	v_lshlrev_b64 v[98:99], 15, v[22:23]
	v_lshlrev_b32_e32 v3, 1, v3
	v_lshl_add_u64 v[22:23], v[6:7], 0, v[98:99]
	v_and_b32_e32 v100, 0x70, v3
	v_lshl_add_u64 v[22:23], v[22:23], 0, v[100:101]
	v_add_u32_e32 v3, 0x140, v9
	global_load_dwordx4 v[126:129], v[22:23], off
	v_ashrrev_i32_e32 v22, 6, v3
	v_ashrrev_i32_e32 v23, 31, v22
	v_lshlrev_b64 v[102:103], 15, v[22:23]
	v_lshl_add_u64 v[22:23], v[6:7], 0, v[102:103]
	v_lshl_add_u64 v[22:23], v[22:23], 0, v[130:131]
	v_add_u32_e32 v3, 0x160, v9
	global_load_dwordx4 v[132:135], v[22:23], off
	v_ashrrev_i32_e32 v22, 6, v3
	v_ashrrev_i32_e32 v23, 31, v22
	v_lshlrev_b64 v[104:105], 15, v[22:23]
	v_lshlrev_b32_e32 v3, 1, v3
	v_lshl_add_u64 v[22:23], v[6:7], 0, v[104:105]
	v_and_b32_e32 v106, 0x70, v3
	v_lshl_add_u64 v[22:23], v[22:23], 0, v[106:107]
	v_add_u32_e32 v3, 0x180, v9
	global_load_dwordx4 v[136:139], v[22:23], off
	v_ashrrev_i32_e32 v22, 6, v3
	v_ashrrev_i32_e32 v23, 31, v22
	v_lshlrev_b64 v[110:111], 15, v[22:23]
	v_lshl_add_u64 v[22:23], v[6:7], 0, v[110:111]
	v_lshl_add_u64 v[22:23], v[22:23], 0, v[130:131]
	v_add_u32_e32 v3, 0x1a0, v9
	global_load_dwordx4 v[140:143], v[22:23], off
	v_ashrrev_i32_e32 v22, 6, v3
	v_ashrrev_i32_e32 v23, 31, v22
	v_lshlrev_b64 v[114:115], 15, v[22:23]
	v_lshlrev_b32_e32 v3, 1, v3
	v_lshl_add_u64 v[22:23], v[6:7], 0, v[114:115]
	v_and_b32_e32 v120, 0x70, v3
	v_lshl_add_u64 v[22:23], v[22:23], 0, v[120:121]
	global_load_dwordx4 v[144:147], v[22:23], off
	v_add_u32_e32 v3, 0x1c0, v9
	v_ashrrev_i32_e32 v22, 6, v3
	v_ashrrev_i32_e32 v23, 31, v22
	v_lshlrev_b64 v[116:117], 15, v[22:23]
	v_lshl_add_u64 v[22:23], v[6:7], 0, v[116:117]
	v_lshl_add_u64 v[22:23], v[22:23], 0, v[130:131]
	v_add_u32_e32 v3, 0x1e0, v9
	global_load_dwordx4 v[148:151], v[22:23], off
	v_ashrrev_i32_e32 v22, 6, v3
	ds_read_b128 v[66:69], v8 offset:16384
	v_ashrrev_i32_e32 v23, 31, v22
	v_lshlrev_b64 v[108:109], 15, v[22:23]
	v_lshlrev_b32_e32 v3, 1, v3
	v_lshl_add_u64 v[6:7], v[6:7], 0, v[108:109]
	v_and_b32_e32 v112, 0x70, v3
	v_lshl_add_u64 v[6:7], v[6:7], 0, v[112:113]
	ds_read_b128 v[22:25], v8 offset:16448
	global_load_dwordx4 v[152:155], v[6:7], off
	ds_read_b128 v[26:29], v8 offset:16512
	ds_read_b128 v[30:33], v8 offset:16576
	s_waitcnt vmcnt(15) lgkmcnt(3)
	v_mfma_f32_16x16x32_bf16 v[10:13], v[66:69], v[10:13], 0
	ds_read_b128 v[38:41], v8 offset:16640
	ds_read_b128 v[54:57], v8 offset:16832
	ds_read_b128 v[62:65], v8 offset:16896
	s_waitcnt vmcnt(14) lgkmcnt(5)
	v_mfma_f32_16x16x32_bf16 v[10:13], v[22:25], v[14:17], v[10:13]
	ds_read_b128 v[14:17], v8 offset:17216
	s_waitcnt vmcnt(13) lgkmcnt(5)
	v_mfma_f32_16x16x32_bf16 v[10:13], v[26:29], v[18:21], v[10:13]
	ds_read_b128 v[18:21], v8 offset:17152
	s_waitcnt vmcnt(12) lgkmcnt(5)
	v_mfma_f32_16x16x32_bf16 v[10:13], v[30:33], v[34:37], v[10:13]
	ds_read_b128 v[34:37], v8 offset:17088
	s_waitcnt vmcnt(11) lgkmcnt(5)
	v_mfma_f32_16x16x32_bf16 v[10:13], v[38:41], v[42:45], v[10:13]
	ds_read_b128 v[42:45], v8 offset:16704
	s_waitcnt vmcnt(10) lgkmcnt(0)
	v_mfma_f32_16x16x32_bf16 v[10:13], v[42:45], v[46:49], v[10:13]
	ds_read_b128 v[46:49], v8 offset:16768
	s_waitcnt vmcnt(9) lgkmcnt(0)
	v_mfma_f32_16x16x32_bf16 v[10:13], v[46:49], v[50:53], v[10:13]
	ds_read_b128 v[50:53], v8 offset:17024
	s_waitcnt vmcnt(8)
	v_mfma_f32_16x16x32_bf16 v[10:13], v[54:57], v[58:61], v[10:13]
	ds_read_b128 v[58:61], v8 offset:16960
	s_waitcnt vmcnt(7)
	v_mfma_f32_16x16x32_bf16 v[10:13], v[62:65], v[70:73], v[10:13]
	s_waitcnt vmcnt(6) lgkmcnt(0)
	v_mfma_f32_16x16x32_bf16 v[10:13], v[58:61], v[126:129], v[10:13]
	s_waitcnt vmcnt(5)
	v_mfma_f32_16x16x32_bf16 v[10:13], v[50:53], v[132:135], v[10:13]
	s_waitcnt vmcnt(4)
	v_mfma_f32_16x16x32_bf16 v[10:13], v[34:37], v[136:139], v[10:13]
	s_waitcnt vmcnt(3)
	v_mfma_f32_16x16x32_bf16 v[10:13], v[18:21], v[140:143], v[10:13]
	s_waitcnt vmcnt(2)
	v_mfma_f32_16x16x32_bf16 v[70:73], v[14:17], v[144:147], v[10:13]
	s_nop 5
	ds_read_b128 v[10:13], v8 offset:17280
	ds_read_b128 v[6:9], v8 offset:17344
	s_waitcnt vmcnt(1) lgkmcnt(1)
	v_mfma_f32_16x16x32_bf16 v[70:73], v[10:13], v[148:151], v[70:73]
	s_waitcnt vmcnt(0) lgkmcnt(0)
; #define GAS __attribute__((address_space(1)))
; #define LAS __attribute__((address_space(3)))
; #define SCAN_STAMP(k) do { if (PROBE_SSM_PART == 3 + (k)) pt0 = __builtin_amdgcn_s_memrealtime(); if (PROBE_SSM_PART == 2 + (k)) pt1 = __builtin_amdgcn_s_memrealtime(); } while (0)
; __device__ __forceinline__ void scan_pair(Frame& F, const int g, const int b, unsigned long long& pt0, unsigned long long& pt1) {
;     ...
;     float h0r = 0.f, h0i = 0.f;
;     {   const LAS f32x4* sre = (const LAS f32x4*)(sctx + (r * 128 + n) * 8); const LAS f32x4* sim = (const LAS f32x4*)(sctx + (r * 128 + 64 + n) * 8);
;         const f32x4 re0 = sre[0], re1 = sre[1], im0 = sim[0], im1 = sim[1];
;         if (r == 0) {
; #pragma unroll
;             for (int c = 0; c < 8; ++c) cmul_acc(h0r, h0i, aTr, aTi, c < 4 ? re0[c & 3] : re1[c & 3], c < 4 ? im0[c & 3] : im1[c & 3]);
;         } else {
; #pragma unroll
;             for (int c = 7; c >= 0; --c) cmul_acc(h0r, h0i, aTr, aTi, c < 4 ? re0[c & 3] : re1[c & 3], c < 4 ? im0[c & 3] : im1[c & 3]); } }
;     SCAN_STAMP(1);
;     constexpr int CPW = NCHB / 4; static_assert(CPW == 128, "scan register blocking");
;     const int cb = b * NCHB + (r ? NCHB - CPW * (wq + 1) : CPW * wq);
;     const bf16* re_row = (const bf16*)(F.ws + WS_S + (size_t)g * MiB) + ((size_t)(cb >> 3) * 256 + r * 128 + n) * 8;
;     const bf16* im_row = re_row + 64 * 8;
;     bf16* Xg = (bf16*)(F.ws + WS_X + (size_t)g * XPLANE) + TP + r * 128 + n;
;     ...
;     LAS bf16* tile = (LAS bf16*)(F.lds + 8192 + F.wave * 1024);
;     GAS char* hp = (GAS char*)(F.ws + WS_X + (size_t)g * XPLANE) + ((size_t)(TP / 64 + 2 * r + ((n & 15) >> 3)) * NCOL + (cb + (r ? CPW - 1 - (n >> 4) : (n >> 4)))) * 128 + (n & 7) * 16;
;     const long hstep4 = (r ? -4L : 4L) * 128;
	v_mfma_f32_16x16x32_bf16 v[70:73], v[6:9], v[152:155], v[70:73]
	s_and_saveexec_b64 s[4:5], vcc
	v_lshl_add_u32 v3, v2, 5, v124
	s_nop 5
	ds_write_b128 v3, v[70:73] offset:24704
	s_or_b64 exec, exec, s[4:5]
	v_or_b32_e32 v2, 16, v2
	v_mov_b32_e32 v3, v131
	v_lshlrev_b64 v[70:71], 7, v[2:3]
	v_lshl_add_u64 v[126:127], s[82:83], 0, v[70:71]
	v_lshl_add_u64 v[70:71], v[126:127], 0, v[76:77]
	v_lshl_add_u64 v[70:71], v[70:71], 0, v[130:131]
	global_load_dwordx4 v[170:173], v[70:71], off
	v_lshl_add_u64 v[70:71], v[126:127], 0, v[118:119]
	v_lshl_add_u64 v[70:71], v[70:71], 0, v[122:123]
	global_load_dwordx4 v[174:177], v[70:71], off
	v_lshl_add_u64 v[70:71], v[126:127], 0, v[78:79]
	v_lshl_add_u64 v[70:71], v[70:71], 0, v[130:131]
	global_load_dwordx4 v[178:181], v[70:71], off
	v_lshl_add_u64 v[70:71], v[126:127], 0, v[80:81]
	v_lshl_add_u64 v[70:71], v[70:71], 0, v[82:83]
	global_load_dwordx4 v[182:185], v[70:71], off
	v_lshl_add_u64 v[70:71], v[126:127], 0, v[84:85]
	v_lshl_add_u64 v[70:71], v[70:71], 0, v[130:131]
	global_load_dwordx4 v[186:189], v[70:71], off
	v_lshl_add_u64 v[70:71], v[126:127], 0, v[86:87]
	v_lshl_add_u64 v[70:71], v[70:71], 0, v[88:89]
	global_load_dwordx4 v[190:193], v[70:71], off
	v_lshl_add_u64 v[70:71], v[126:127], 0, v[90:91]
	v_lshl_add_u64 v[70:71], v[70:71], 0, v[130:131]
	global_load_dwordx4 v[194:197], v[70:71], off
	v_lshl_add_u64 v[70:71], v[126:127], 0, v[92:93]
	v_lshl_add_u64 v[70:71], v[70:71], 0, v[94:95]
	global_load_dwordx4 v[198:201], v[70:71], off
	v_lshl_add_u64 v[70:71], v[126:127], 0, v[96:97]
	v_lshl_add_u64 v[70:71], v[70:71], 0, v[130:131]
	global_load_dwordx4 v[202:205], v[70:71], off
	v_lshl_add_u64 v[70:71], v[126:127], 0, v[98:99]
	v_lshl_add_u64 v[70:71], v[70:71], 0, v[100:101]
	global_load_dwordx4 v[210:213], v[70:71], off
	v_lshl_add_u64 v[70:71], v[126:127], 0, v[102:103]
	v_lshl_add_u64 v[70:71], v[70:71], 0, v[130:131]
	global_load_dwordx4 v[214:217], v[70:71], off
	v_lshl_add_u64 v[70:71], v[126:127], 0, v[104:105]
	v_lshl_add_u64 v[70:71], v[70:71], 0, v[106:107]
	global_load_dwordx4 v[218:221], v[70:71], off
	v_lshl_add_u64 v[70:71], v[126:127], 0, v[110:111]
	v_lshl_add_u64 v[70:71], v[70:71], 0, v[130:131]
	global_load_dwordx4 v[222:225], v[70:71], off
	v_lshl_add_u64 v[70:71], v[126:127], 0, v[114:115]
	v_lshl_add_u64 v[70:71], v[70:71], 0, v[120:121]
	global_load_dwordx4 v[226:229], v[70:71], off
	v_lshl_add_u64 v[70:71], v[126:127], 0, v[116:117]
	v_lshl_add_u64 v[70:71], v[70:71], 0, v[130:131]
	global_load_dwordx4 v[230:233], v[70:71], off
	v_lshl_add_u64 v[70:71], v[126:127], 0, v[108:109]
	v_lshl_add_u64 v[70:71], v[70:71], 0, v[112:113]
	global_load_dwordx4 v[234:237], v[70:71], off
	s_waitcnt vmcnt(15)
	v_mfma_f32_16x16x32_bf16 v[66:69], v[66:69], v[170:173], 0
	s_waitcnt vmcnt(14)
	v_mfma_f32_16x16x32_bf16 v[22:25], v[22:25], v[174:177], v[66:69]
	s_waitcnt vmcnt(13)
	v_mfma_f32_16x16x32_bf16 v[22:25], v[26:29], v[178:181], v[22:25]
	s_waitcnt vmcnt(12)
	v_mfma_f32_16x16x32_bf16 v[22:25], v[30:33], v[182:185], v[22:25]
	s_waitcnt vmcnt(11)
	v_mfma_f32_16x16x32_bf16 v[22:25], v[38:41], v[186:189], v[22:25]
	s_waitcnt vmcnt(10)
	v_mfma_f32_16x16x32_bf16 v[22:25], v[42:45], v[190:193], v[22:25]
	s_waitcnt vmcnt(9)
	v_mfma_f32_16x16x32_bf16 v[22:25], v[46:49], v[194:197], v[22:25]
	s_waitcnt vmcnt(8)
	v_mfma_f32_16x16x32_bf16 v[22:25], v[54:57], v[198:201], v[22:25]
	s_waitcnt vmcnt(7)
	v_mfma_f32_16x16x32_bf16 v[22:25], v[62:65], v[202:205], v[22:25]
	s_waitcnt vmcnt(6)
	v_mfma_f32_16x16x32_bf16 v[22:25], v[58:61], v[210:213], v[22:25]
	s_waitcnt vmcnt(5)
	v_mfma_f32_16x16x32_bf16 v[22:25], v[50:53], v[214:217], v[22:25]
	s_waitcnt vmcnt(4)
	v_mfma_f32_16x16x32_bf16 v[22:25], v[34:37], v[218:221], v[22:25]
	s_waitcnt vmcnt(3)
	v_mfma_f32_16x16x32_bf16 v[18:21], v[18:21], v[222:225], v[22:25]
	s_waitcnt vmcnt(2)
	v_mfma_f32_16x16x32_bf16 v[14:17], v[14:17], v[226:229], v[18:21]
	s_waitcnt vmcnt(1)
	v_mfma_f32_16x16x32_bf16 v[10:13], v[10:13], v[230:233], v[14:17]
	s_waitcnt vmcnt(0)
	v_mfma_f32_16x16x32_bf16 v[6:9], v[6:9], v[234:237], v[10:13]
	s_and_saveexec_b64 s[4:5], vcc
	v_readlane_b32 s14, v253, 59
	v_readlane_b32 s15, v253, 60
	v_lshl_add_u32 v2, v2, 5, v124
	s_nop 3
	ds_write_b128 v2, v[6:9] offset:24704
	s_or_b64 exec, exec, s[4:5]
	v_add_u32_e32 v2, s10, v74
	v_lshl_add_u32 v2, v2, 5, 0
	s_waitcnt lgkmcnt(0)
	s_barrier
	v_readlane_b32 s4, v253, 23
	s_nop 3
	s_lshr_b32 s5, s4, 2
	s_and_b32 s6, s4, 3
	s_lshl_b32 s7, s6, 7
	s_sub_i32 s16, 0x180, s7
	s_cmp_eq_u32 s5, 0
	s_cselect_b32 s7, s7, s16
	s_lshl_b32 s2, s2, 9
	s_add_i32 s2, s2, s7
	s_lshr_b32 s7, s2, 3
	s_lshl_b32 s7, s7, 12
	s_lshl_b32 s16, s5, 11
	s_add_i32 s7, s7, s16
	s_mul_i32 s16, s5, 0xf000
	s_add_i32 s7, s7, s16
	s_add_u32 s68, s80, s7
	s_addc_u32 s69, s81, 0
	s_lshl_b32 s7, s5, 18
	s_add_i32 s7, s7, 0x100000
	s_lshl_b32 s16, s2, 7
	s_add_i32 s7, s7, s16
	s_add_u32 s28, s62, s7
	s_addc_u32 s29, s63, 0
	v_lshlrev_b32_e32 v30, 4, v209
	v_lshrrev_b32_e32 v31, 4, v209
	v_sub_u32_e32 v37, 0x7f, v31
	s_cmp_eq_u32 s5, 0
	s_cselect_b64 vcc, -1, 0
	s_nop 3
	v_cndmask_b32_e32 v31, v37, v31, vcc
	v_lshlrev_b32_e32 v31, 7, v31
	v_and_b32_e32 v37, 7, v209
	v_lshl_add_u32 v31, v37, 4, v31
	v_bfe_u32 v37, v209, 3, 1
	v_lshl_add_u32 v31, v37, 17, v31
	s_lshl_b32 s7, s4, 10
	s_add_i32 s7, s7, 0x2000
	v_lshl_add_u32 v32, v209, 2, s7
	v_lshl_add_u32 v33, v209, 4, s7
	s_lshl_b32 s7, s4, 9
	v_lshl_add_u32 v34, v209, 3, s7
	s_lshl_b32 s7, s5, 11
	v_lshl_add_u32 v35, v209, 3, s7
	s_lshl_b32 s7, s5, 7
	v_add_u32_e32 v36, s7, v209
	v_lshlrev_b32_e32 v36, 5, v36
	ds_read_b128 v[80:83], v36 offset:24704
	ds_read_b128 v[84:87], v36 offset:24720
	ds_read_b128 v[88:91], v36 offset:26752
	ds_read_b128 v[92:95], v36 offset:26768
	v_mov_b32_e32 v10, 0
	v_mov_b32_e32 v11, 0
	s_waitcnt lgkmcnt(0)
	s_cmp_lg_u32 s5, 0
	s_cbranch_scc1 .Lsc_ctx1
; #define LAS __attribute__((address_space(3)))
; #define SCAN_STAMP(k) do { if (PROBE_SSM_PART == 3 + (k)) pt0 = __builtin_amdgcn_s_memrealtime(); if (PROBE_SSM_PART == 2 + (k)) pt1 = __builtin_amdgcn_s_memrealtime(); } while (0)
; #define SCAN_LOAD(HALF) do { _Pragma("unroll") for (int k = 0; k < 8; ++k) { const int kk = r ? (15 - 8 * (HALF) - k) : (8 * (HALF) + k); pre[k] = *(const u32x4*)(re_row + 2048 * kk); pim[k] = *(const u32x4*)(im_row + 2048 * kk); } } while (0)
; __device__ __forceinline__ void scan_pair(Frame& F, const int g, const int b, unsigned long long& pt0, unsigned long long& pt1) {
;     ...
;     float h0r = 0.f, h0i = 0.f;
;     {   const LAS f32x4* sre = (const LAS f32x4*)(sctx + (r * 128 + n) * 8); const LAS f32x4* sim = (const LAS f32x4*)(sctx + (r * 128 + 64 + n) * 8);
;         const f32x4 re0 = sre[0], re1 = sre[1], im0 = sim[0], im1 = sim[1];
;         if (r == 0) {
; #pragma unroll
;             for (int c = 0; c < 8; ++c) cmul_acc(h0r, h0i, aTr, aTi, c < 4 ? re0[c & 3] : re1[c & 3], c < 4 ? im0[c & 3] : im1[c & 3]);
;         } else {
; #pragma unroll
;             for (int c = 7; c >= 0; --c) cmul_acc(h0r, h0i, aTr, aTi, c < 4 ? re0[c & 3] : re1[c & 3], c < 4 ? im0[c & 3] : im1[c & 3]); } }
;     SCAN_STAMP(1);
;     constexpr int CPW = NCHB / 4; static_assert(CPW == 128, "scan register blocking");
;     const int cb = b * NCHB + (r ? NCHB - CPW * (wq + 1) : CPW * wq);
;     const bf16* re_row = (const bf16*)(F.ws + WS_S + (size_t)g * MiB) + ((size_t)(cb >> 3) * 256 + r * 128 + n) * 8;
;     const bf16* im_row = re_row + 64 * 8;
;     bf16* Xg = (bf16*)(F.ws + WS_X + (size_t)g * XPLANE) + TP + r * 128 + n;
;     ...
;     u32x4 pre[8], pim[8];
;     float er = 0.f, ei = 0.f;
; #pragma unroll
;     for (int half = 0; half < 2; ++half) { SCAN_LOAD(half);
;         if (r == 0) {
; #pragma unroll
;             for (int i = 0; i < 64; ++i) cmul_acc(er, ei, aTr, aTi, bf2f(pre[i >> 3][(i & 7) >> 1] >> (16 * (i & 1))), bf2f(pim[i >> 3][(i & 7) >> 1] >> (16 * (i & 1))));
;         } else {
; #pragma unroll
;             for (int i = 0; i < 64; ++i) { const int e = 7 - (i & 7); cmul_acc(er, ei, aTr, aTi, bf2f(pre[i >> 3][e >> 1] >> (16 * (e & 1))), bf2f(pim[i >> 3][e >> 1] >> (16 * (e & 1)))); }
;         }
;         asm volatile("" ::: "memory"); }
	v_mul_f32_e32 v12, v249, v11
	v_mul_f32_e32 v13, v248, v11
	v_fma_f32 v14, v248, v10, -v12
	v_fma_f32 v15, v249, v10, v13
	v_add_f32_e32 v10, v14, v80
	v_add_f32_e32 v11, v15, v88
	v_mul_f32_e32 v12, v249, v11
	v_mul_f32_e32 v13, v248, v11
	v_fma_f32 v14, v248, v10, -v12
	v_fma_f32 v15, v249, v10, v13
	v_add_f32_e32 v10, v14, v81
	v_add_f32_e32 v11, v15, v89
	v_mul_f32_e32 v12, v249, v11
	v_mul_f32_e32 v13, v248, v11
	v_fma_f32 v14, v248, v10, -v12
	v_fma_f32 v15, v249, v10, v13
	v_add_f32_e32 v10, v14, v82
	v_add_f32_e32 v11, v15, v90
	v_mul_f32_e32 v12, v249, v11
	v_mul_f32_e32 v13, v248, v11
	v_fma_f32 v14, v248, v10, -v12
	v_fma_f32 v15, v249, v10, v13
	v_add_f32_e32 v10, v14, v83
	v_add_f32_e32 v11, v15, v91
	v_mul_f32_e32 v12, v249, v11
	v_mul_f32_e32 v13, v248, v11
	v_fma_f32 v14, v248, v10, -v12
	v_fma_f32 v15, v249, v10, v13
	v_add_f32_e32 v10, v14, v84
	v_add_f32_e32 v11, v15, v92
	v_mul_f32_e32 v12, v249, v11
	v_mul_f32_e32 v13, v248, v11
	v_fma_f32 v14, v248, v10, -v12
	v_fma_f32 v15, v249, v10, v13
	v_add_f32_e32 v10, v14, v85
	v_add_f32_e32 v11, v15, v93
	v_mul_f32_e32 v12, v249, v11
	v_mul_f32_e32 v13, v248, v11
	v_fma_f32 v14, v248, v10, -v12
	v_fma_f32 v15, v249, v10, v13
	v_add_f32_e32 v10, v14, v86
	v_add_f32_e32 v11, v15, v94
	v_mul_f32_e32 v12, v249, v11
	v_mul_f32_e32 v13, v248, v11
	v_fma_f32 v14, v248, v10, -v12
	v_fma_f32 v15, v249, v10, v13
	v_add_f32_e32 v10, v14, v87
	v_add_f32_e32 v11, v15, v95
	s_branch .Lsc_ctxd
.Lsc_ctx1:
	v_mul_f32_e32 v12, v249, v11
	v_mul_f32_e32 v13, v248, v11
	v_fma_f32 v14, v248, v10, -v12
	v_fma_f32 v15, v249, v10, v13
	v_add_f32_e32 v10, v14, v87
	v_add_f32_e32 v11, v15, v95
	v_mul_f32_e32 v12, v249, v11
	v_mul_f32_e32 v13, v248, v11
	v_fma_f32 v14, v248, v10, -v12
	v_fma_f32 v15, v249, v10, v13
	v_add_f32_e32 v10, v14, v86
	v_add_f32_e32 v11, v15, v94
	v_mul_f32_e32 v12, v249, v11
	v_mul_f32_e32 v13, v248, v11
	v_fma_f32 v14, v248, v10, -v12
	v_fma_f32 v15, v249, v10, v13
	v_add_f32_e32 v10, v14, v85
	v_add_f32_e32 v11, v15, v93
	v_mul_f32_e32 v12, v249, v11
	v_mul_f32_e32 v13, v248, v11
	v_fma_f32 v14, v248, v10, -v12
	v_fma_f32 v15, v249, v10, v13
	v_add_f32_e32 v10, v14, v84
	v_add_f32_e32 v11, v15, v92
	v_mul_f32_e32 v12, v249, v11
	v_mul_f32_e32 v13, v248, v11
	v_fma_f32 v14, v248, v10, -v12
	v_fma_f32 v15, v249, v10, v13
	v_add_f32_e32 v10, v14, v83
	v_add_f32_e32 v11, v15, v91
	v_mul_f32_e32 v12, v249, v11
	v_mul_f32_e32 v13, v248, v11
	v_fma_f32 v14, v248, v10, -v12
	v_fma_f32 v15, v249, v10, v13
	v_add_f32_e32 v10, v14, v82
	v_add_f32_e32 v11, v15, v90
	v_mul_f32_e32 v12, v249, v11
	v_mul_f32_e32 v13, v248, v11
	v_fma_f32 v14, v248, v10, -v12
	v_fma_f32 v15, v249, v10, v13
	v_add_f32_e32 v10, v14, v81
	v_add_f32_e32 v11, v15, v89
	v_mul_f32_e32 v12, v249, v11
	v_mul_f32_e32 v13, v248, v11
	v_fma_f32 v14, v248, v10, -v12
	v_fma_f32 v15, v249, v10, v13
	v_add_f32_e32 v10, v14, v80
	v_add_f32_e32 v11, v15, v88
.Lsc_ctxd:
	v_mov_b32_e32 v20, v10
	v_mov_b32_e32 v21, v11
	v_mov_b32_e32 v10, 0
	v_mov_b32_e32 v11, 0
	s_cmp_lg_u32 s5, 0
	s_cbranch_scc1 .Lsc_p1r1
	s_mov_b64 s[10:11], s[68:69]
	global_load_dwordx4 v[40:43], v30, s[10:11]
	global_load_dwordx4 v[44:47], v30, s[10:11] offset:1024
	s_add_u32 s10, s10, 0x1000
	s_addc_u32 s11, s11, 0
	global_load_dwordx4 v[48:51], v30, s[10:11]
	global_load_dwordx4 v[52:55], v30, s[10:11] offset:1024
	s_add_u32 s10, s10, 0x1000
	s_addc_u32 s11, s11, 0
	global_load_dwordx4 v[56:59], v30, s[10:11]
	global_load_dwordx4 v[60:63], v30, s[10:11] offset:1024
	s_add_u32 s10, s10, 0x1000
	s_addc_u32 s11, s11, 0
	global_load_dwordx4 v[64:67], v30, s[10:11]
	global_load_dwordx4 v[68:71], v30, s[10:11] offset:1024
	s_add_u32 s10, s10, 0x1000
	s_addc_u32 s11, s11, 0
	s_waitcnt vmcnt(0)
	s_mov_b32 s16, 4
.Lscl_p1r0:
	s_waitcnt vmcnt(6)
	v_lshlrev_b32_e32 v16, 16, v40
	v_lshlrev_b32_e32 v17, 16, v44
	v_mul_f32_e32 v12, v249, v11
	v_mul_f32_e32 v13, v248, v11
	v_fma_f32 v14, v248, v10, -v12
	v_fma_f32 v15, v249, v10, v13
	v_add_f32_e32 v10, v14, v16
	v_add_f32_e32 v11, v15, v17
	v_and_b32_e32 v16, 0xffff0000, v40
	v_and_b32_e32 v17, 0xffff0000, v44
	v_mul_f32_e32 v12, v249, v11
	v_mul_f32_e32 v13, v248, v11
	v_fma_f32 v14, v248, v10, -v12
	v_fma_f32 v15, v249, v10, v13
	v_add_f32_e32 v10, v14, v16
	v_add_f32_e32 v11, v15, v17
	v_lshlrev_b32_e32 v16, 16, v41
	v_lshlrev_b32_e32 v17, 16, v45
	v_mul_f32_e32 v12, v249, v11
	v_mul_f32_e32 v13, v248, v11
	v_fma_f32 v14, v248, v10, -v12
	v_fma_f32 v15, v249, v10, v13
	v_add_f32_e32 v10, v14, v16
	v_add_f32_e32 v11, v15, v17
	v_and_b32_e32 v16, 0xffff0000, v41
	v_and_b32_e32 v17, 0xffff0000, v45
	v_mul_f32_e32 v12, v249, v11
	v_mul_f32_e32 v13, v248, v11
	v_fma_f32 v14, v248, v10, -v12
	v_fma_f32 v15, v249, v10, v13
	v_add_f32_e32 v10, v14, v16
	v_add_f32_e32 v11, v15, v17
	v_lshlrev_b32_e32 v16, 16, v42
	v_lshlrev_b32_e32 v17, 16, v46
	v_mul_f32_e32 v12, v249, v11
	v_mul_f32_e32 v13, v248, v11
	v_fma_f32 v14, v248, v10, -v12
	v_fma_f32 v15, v249, v10, v13
	v_add_f32_e32 v10, v14, v16
	v_add_f32_e32 v11, v15, v17
	v_and_b32_e32 v16, 0xffff0000, v42
	v_and_b32_e32 v17, 0xffff0000, v46
	v_mul_f32_e32 v12, v249, v11
	v_mul_f32_e32 v13, v248, v11
	v_fma_f32 v14, v248, v10, -v12
	v_fma_f32 v15, v249, v10, v13
	v_add_f32_e32 v10, v14, v16
	v_add_f32_e32 v11, v15, v17
	v_lshlrev_b32_e32 v16, 16, v43
	v_lshlrev_b32_e32 v17, 16, v47
	v_mul_f32_e32 v12, v249, v11
	v_mul_f32_e32 v13, v248, v11
	v_fma_f32 v14, v248, v10, -v12
	v_fma_f32 v15, v249, v10, v13
	v_add_f32_e32 v10, v14, v16
	v_add_f32_e32 v11, v15, v17
	v_and_b32_e32 v16, 0xffff0000, v43
	v_and_b32_e32 v17, 0xffff0000, v47
	v_mul_f32_e32 v12, v249, v11
	v_mul_f32_e32 v13, v248, v11
	v_fma_f32 v14, v248, v10, -v12
	v_fma_f32 v15, v249, v10, v13
	v_add_f32_e32 v10, v14, v16
	v_add_f32_e32 v11, v15, v17
	global_load_dwordx4 v[40:43], v30, s[10:11]
	global_load_dwordx4 v[44:47], v30, s[10:11] offset:1024
	s_add_u32 s10, s10, 0x1000
	s_addc_u32 s11, s11, 0
	s_waitcnt vmcnt(6)
; #define SCAN_LOAD(HALF) do { _Pragma("unroll") for (int k = 0; k < 8; ++k) { const int kk = r ? (15 - 8 * (HALF) - k) : (8 * (HALF) + k); pre[k] = *(const u32x4*)(re_row + 2048 * kk); pim[k] = *(const u32x4*)(im_row + 2048 * kk); } } while (0)
; __device__ __forceinline__ void scan_pair(Frame& F, const int g, const int b, unsigned long long& pt0, unsigned long long& pt1) {
;     ...
;     u32x4 pre[8], pim[8];
;     float er = 0.f, ei = 0.f;
; #pragma unroll
;     for (int half = 0; half < 2; ++half) { SCAN_LOAD(half);
;         if (r == 0) {
; #pragma unroll
;             for (int i = 0; i < 64; ++i) cmul_acc(er, ei, aTr, aTi, bf2f(pre[i >> 3][(i & 7) >> 1] >> (16 * (i & 1))), bf2f(pim[i >> 3][(i & 7) >> 1] >> (16 * (i & 1))));
;         } else {
; #pragma unroll
;             for (int i = 0; i < 64; ++i) { const int e = 7 - (i & 7); cmul_acc(er, ei, aTr, aTi, bf2f(pre[i >> 3][e >> 1] >> (16 * (e & 1))), bf2f(pim[i >> 3][e >> 1] >> (16 * (e & 1)))); }
;         }
;         asm volatile("" ::: "memory"); }
	v_lshlrev_b32_e32 v16, 16, v48
	v_lshlrev_b32_e32 v17, 16, v52
	v_mul_f32_e32 v12, v249, v11
	v_mul_f32_e32 v13, v248, v11
	v_fma_f32 v14, v248, v10, -v12
	v_fma_f32 v15, v249, v10, v13
	v_add_f32_e32 v10, v14, v16
	v_add_f32_e32 v11, v15, v17
	v_and_b32_e32 v16, 0xffff0000, v48
	v_and_b32_e32 v17, 0xffff0000, v52
	v_mul_f32_e32 v12, v249, v11
	v_mul_f32_e32 v13, v248, v11
	v_fma_f32 v14, v248, v10, -v12
	v_fma_f32 v15, v249, v10, v13
	v_add_f32_e32 v10, v14, v16
	v_add_f32_e32 v11, v15, v17
	v_lshlrev_b32_e32 v16, 16, v49
	v_lshlrev_b32_e32 v17, 16, v53
	v_mul_f32_e32 v12, v249, v11
	v_mul_f32_e32 v13, v248, v11
	v_fma_f32 v14, v248, v10, -v12
	v_fma_f32 v15, v249, v10, v13
	v_add_f32_e32 v10, v14, v16
	v_add_f32_e32 v11, v15, v17
	v_and_b32_e32 v16, 0xffff0000, v49
	v_and_b32_e32 v17, 0xffff0000, v53
	v_mul_f32_e32 v12, v249, v11
	v_mul_f32_e32 v13, v248, v11
	v_fma_f32 v14, v248, v10, -v12
	v_fma_f32 v15, v249, v10, v13
	v_add_f32_e32 v10, v14, v16
	v_add_f32_e32 v11, v15, v17
	v_lshlrev_b32_e32 v16, 16, v50
	v_lshlrev_b32_e32 v17, 16, v54
	v_mul_f32_e32 v12, v249, v11
	v_mul_f32_e32 v13, v248, v11
	v_fma_f32 v14, v248, v10, -v12
	v_fma_f32 v15, v249, v10, v13
	v_add_f32_e32 v10, v14, v16
	v_add_f32_e32 v11, v15, v17
	v_and_b32_e32 v16, 0xffff0000, v50
	v_and_b32_e32 v17, 0xffff0000, v54
	v_mul_f32_e32 v12, v249, v11
	v_mul_f32_e32 v13, v248, v11
	v_fma_f32 v14, v248, v10, -v12
	v_fma_f32 v15, v249, v10, v13
	v_add_f32_e32 v10, v14, v16
	v_add_f32_e32 v11, v15, v17
	v_lshlrev_b32_e32 v16, 16, v51
	v_lshlrev_b32_e32 v17, 16, v55
	v_mul_f32_e32 v12, v249, v11
	v_mul_f32_e32 v13, v248, v11
	v_fma_f32 v14, v248, v10, -v12
	v_fma_f32 v15, v249, v10, v13
	v_add_f32_e32 v10, v14, v16
	v_add_f32_e32 v11, v15, v17
	v_and_b32_e32 v16, 0xffff0000, v51
	v_and_b32_e32 v17, 0xffff0000, v55
	v_mul_f32_e32 v12, v249, v11
	v_mul_f32_e32 v13, v248, v11
	v_fma_f32 v14, v248, v10, -v12
	v_fma_f32 v15, v249, v10, v13
	v_add_f32_e32 v10, v14, v16
	v_add_f32_e32 v11, v15, v17
	global_load_dwordx4 v[48:51], v30, s[10:11]
	global_load_dwordx4 v[52:55], v30, s[10:11] offset:1024
	s_add_u32 s10, s10, 0x1000
	s_addc_u32 s11, s11, 0
	s_waitcnt vmcnt(6)
	v_lshlrev_b32_e32 v16, 16, v56
	v_lshlrev_b32_e32 v17, 16, v60
	v_mul_f32_e32 v12, v249, v11
	v_mul_f32_e32 v13, v248, v11
	v_fma_f32 v14, v248, v10, -v12
	v_fma_f32 v15, v249, v10, v13
	v_add_f32_e32 v10, v14, v16
	v_add_f32_e32 v11, v15, v17
	v_and_b32_e32 v16, 0xffff0000, v56
	v_and_b32_e32 v17, 0xffff0000, v60
	v_mul_f32_e32 v12, v249, v11
	v_mul_f32_e32 v13, v248, v11
	v_fma_f32 v14, v248, v10, -v12
	v_fma_f32 v15, v249, v10, v13
	v_add_f32_e32 v10, v14, v16
	v_add_f32_e32 v11, v15, v17
	v_lshlrev_b32_e32 v16, 16, v57
	v_lshlrev_b32_e32 v17, 16, v61
	v_mul_f32_e32 v12, v249, v11
	v_mul_f32_e32 v13, v248, v11
	v_fma_f32 v14, v248, v10, -v12
	v_fma_f32 v15, v249, v10, v13
	v_add_f32_e32 v10, v14, v16
	v_add_f32_e32 v11, v15, v17
	v_and_b32_e32 v16, 0xffff0000, v57
	v_and_b32_e32 v17, 0xffff0000, v61
	v_mul_f32_e32 v12, v249, v11
	v_mul_f32_e32 v13, v248, v11
	v_fma_f32 v14, v248, v10, -v12
	v_fma_f32 v15, v249, v10, v13
	v_add_f32_e32 v10, v14, v16
	v_add_f32_e32 v11, v15, v17
	v_lshlrev_b32_e32 v16, 16, v58
	v_lshlrev_b32_e32 v17, 16, v62
	v_mul_f32_e32 v12, v249, v11
	v_mul_f32_e32 v13, v248, v11
	v_fma_f32 v14, v248, v10, -v12
	v_fma_f32 v15, v249, v10, v13
	v_add_f32_e32 v10, v14, v16
	v_add_f32_e32 v11, v15, v17
	v_and_b32_e32 v16, 0xffff0000, v58
	v_and_b32_e32 v17, 0xffff0000, v62
	v_mul_f32_e32 v12, v249, v11
	v_mul_f32_e32 v13, v248, v11
	v_fma_f32 v14, v248, v10, -v12
	v_fma_f32 v15, v249, v10, v13
	v_add_f32_e32 v10, v14, v16
	v_add_f32_e32 v11, v15, v17
	v_lshlrev_b32_e32 v16, 16, v59
	v_lshlrev_b32_e32 v17, 16, v63
	v_mul_f32_e32 v12, v249, v11
	v_mul_f32_e32 v13, v248, v11
	v_fma_f32 v14, v248, v10, -v12
	v_fma_f32 v15, v249, v10, v13
	v_add_f32_e32 v10, v14, v16
	v_add_f32_e32 v11, v15, v17
	v_and_b32_e32 v16, 0xffff0000, v59
	v_and_b32_e32 v17, 0xffff0000, v63
	v_mul_f32_e32 v12, v249, v11
	v_mul_f32_e32 v13, v248, v11
	v_fma_f32 v14, v248, v10, -v12
	v_fma_f32 v15, v249, v10, v13
	v_add_f32_e32 v10, v14, v16
	v_add_f32_e32 v11, v15, v17
	global_load_dwordx4 v[56:59], v30, s[10:11]
	global_load_dwordx4 v[60:63], v30, s[10:11] offset:1024
	s_add_u32 s10, s10, 0x1000
	s_addc_u32 s11, s11, 0
	s_waitcnt vmcnt(6)
	v_lshlrev_b32_e32 v16, 16, v64
	v_lshlrev_b32_e32 v17, 16, v68
	v_mul_f32_e32 v12, v249, v11
	v_mul_f32_e32 v13, v248, v11
	v_fma_f32 v14, v248, v10, -v12
	v_fma_f32 v15, v249, v10, v13
	v_add_f32_e32 v10, v14, v16
	v_add_f32_e32 v11, v15, v17
	v_and_b32_e32 v16, 0xffff0000, v64
	v_and_b32_e32 v17, 0xffff0000, v68
	v_mul_f32_e32 v12, v249, v11
	v_mul_f32_e32 v13, v248, v11
	v_fma_f32 v14, v248, v10, -v12
	v_fma_f32 v15, v249, v10, v13
	v_add_f32_e32 v10, v14, v16
	v_add_f32_e32 v11, v15, v17
	v_lshlrev_b32_e32 v16, 16, v65
	v_lshlrev_b32_e32 v17, 16, v69
	v_mul_f32_e32 v12, v249, v11
	v_mul_f32_e32 v13, v248, v11
	v_fma_f32 v14, v248, v10, -v12
	v_fma_f32 v15, v249, v10, v13
	v_add_f32_e32 v10, v14, v16
	v_add_f32_e32 v11, v15, v17
	v_and_b32_e32 v16, 0xffff0000, v65
	v_and_b32_e32 v17, 0xffff0000, v69
	v_mul_f32_e32 v12, v249, v11
	v_mul_f32_e32 v13, v248, v11
	v_fma_f32 v14, v248, v10, -v12
	v_fma_f32 v15, v249, v10, v13
	v_add_f32_e32 v10, v14, v16
	v_add_f32_e32 v11, v15, v17
	v_lshlrev_b32_e32 v16, 16, v66
	v_lshlrev_b32_e32 v17, 16, v70
	v_mul_f32_e32 v12, v249, v11
	v_mul_f32_e32 v13, v248, v11
	v_fma_f32 v14, v248, v10, -v12
	v_fma_f32 v15, v249, v10, v13
	v_add_f32_e32 v10, v14, v16
	v_add_f32_e32 v11, v15, v17
	v_and_b32_e32 v16, 0xffff0000, v66
	v_and_b32_e32 v17, 0xffff0000, v70
	v_mul_f32_e32 v12, v249, v11
	v_mul_f32_e32 v13, v248, v11
	v_fma_f32 v14, v248, v10, -v12
	v_fma_f32 v15, v249, v10, v13
	v_add_f32_e32 v10, v14, v16
	v_add_f32_e32 v11, v15, v17
	v_lshlrev_b32_e32 v16, 16, v67
	v_lshlrev_b32_e32 v17, 16, v71
	v_mul_f32_e32 v12, v249, v11
	v_mul_f32_e32 v13, v248, v11
	v_fma_f32 v14, v248, v10, -v12
	v_fma_f32 v15, v249, v10, v13
	v_add_f32_e32 v10, v14, v16
	v_add_f32_e32 v11, v15, v17
	v_and_b32_e32 v16, 0xffff0000, v67
	v_and_b32_e32 v17, 0xffff0000, v71
	v_mul_f32_e32 v12, v249, v11
	v_mul_f32_e32 v13, v248, v11
	v_fma_f32 v14, v248, v10, -v12
	v_fma_f32 v15, v249, v10, v13
	v_add_f32_e32 v10, v14, v16
	v_add_f32_e32 v11, v15, v17
	global_load_dwordx4 v[64:67], v30, s[10:11]
	global_load_dwordx4 v[68:71], v30, s[10:11] offset:1024
	s_add_u32 s10, s10, 0x1000
	s_addc_u32 s11, s11, 0
	s_sub_i32 s16, s16, 1
	s_cmp_lg_u32 s16, 0
	s_cbranch_scc1 .Lscl_p1r0
	s_waitcnt vmcnt(0)
	s_branch .Lsc_mid
; #define SCAN_LOAD(HALF) do { _Pragma("unroll") for (int k = 0; k < 8; ++k) { const int kk = r ? (15 - 8 * (HALF) - k) : (8 * (HALF) + k); pre[k] = *(const u32x4*)(re_row + 2048 * kk); pim[k] = *(const u32x4*)(im_row + 2048 * kk); } } while (0)
; __device__ __forceinline__ void scan_pair(Frame& F, const int g, const int b, unsigned long long& pt0, unsigned long long& pt1) {
;     ...
;     u32x4 pre[8], pim[8];
;     float er = 0.f, ei = 0.f;
; #pragma unroll
;     for (int half = 0; half < 2; ++half) { SCAN_LOAD(half);
;         if (r == 0) {
; #pragma unroll
;             for (int i = 0; i < 64; ++i) cmul_acc(er, ei, aTr, aTi, bf2f(pre[i >> 3][(i & 7) >> 1] >> (16 * (i & 1))), bf2f(pim[i >> 3][(i & 7) >> 1] >> (16 * (i & 1))));
;         } else {
; #pragma unroll
;             for (int i = 0; i < 64; ++i) { const int e = 7 - (i & 7); cmul_acc(er, ei, aTr, aTi, bf2f(pre[i >> 3][e >> 1] >> (16 * (e & 1))), bf2f(pim[i >> 3][e >> 1] >> (16 * (e & 1)))); }
;         }
;         asm volatile("" ::: "memory"); }
.Lsc_p1r1:
	s_mov_b64 s[10:11], s[68:69]
	global_load_dwordx4 v[40:43], v30, s[10:11]
	global_load_dwordx4 v[44:47], v30, s[10:11] offset:1024
	s_sub_u32 s10, s10, 0x1000
	s_subb_u32 s11, s11, 0
	global_load_dwordx4 v[48:51], v30, s[10:11]
	global_load_dwordx4 v[52:55], v30, s[10:11] offset:1024
	s_sub_u32 s10, s10, 0x1000
	s_subb_u32 s11, s11, 0
	global_load_dwordx4 v[56:59], v30, s[10:11]
	global_load_dwordx4 v[60:63], v30, s[10:11] offset:1024
	s_sub_u32 s10, s10, 0x1000
	s_subb_u32 s11, s11, 0
	global_load_dwordx4 v[64:67], v30, s[10:11]
	global_load_dwordx4 v[68:71], v30, s[10:11] offset:1024
	s_sub_u32 s10, s10, 0x1000
	s_subb_u32 s11, s11, 0
	s_waitcnt vmcnt(0)
	s_mov_b32 s16, 4
.Lscl_p1r1:
	s_waitcnt vmcnt(6)
	v_and_b32_e32 v16, 0xffff0000, v43
	v_and_b32_e32 v17, 0xffff0000, v47
	v_mul_f32_e32 v12, v249, v11
	v_mul_f32_e32 v13, v248, v11
	v_fma_f32 v14, v248, v10, -v12
	v_fma_f32 v15, v249, v10, v13
	v_add_f32_e32 v10, v14, v16
	v_add_f32_e32 v11, v15, v17
	v_lshlrev_b32_e32 v16, 16, v43
	v_lshlrev_b32_e32 v17, 16, v47
	v_mul_f32_e32 v12, v249, v11
	v_mul_f32_e32 v13, v248, v11
	v_fma_f32 v14, v248, v10, -v12
	v_fma_f32 v15, v249, v10, v13
	v_add_f32_e32 v10, v14, v16
	v_add_f32_e32 v11, v15, v17
	v_and_b32_e32 v16, 0xffff0000, v42
	v_and_b32_e32 v17, 0xffff0000, v46
	v_mul_f32_e32 v12, v249, v11
	v_mul_f32_e32 v13, v248, v11
	v_fma_f32 v14, v248, v10, -v12
	v_fma_f32 v15, v249, v10, v13
	v_add_f32_e32 v10, v14, v16
	v_add_f32_e32 v11, v15, v17
	v_lshlrev_b32_e32 v16, 16, v42
	v_lshlrev_b32_e32 v17, 16, v46
	v_mul_f32_e32 v12, v249, v11
	v_mul_f32_e32 v13, v248, v11
	v_fma_f32 v14, v248, v10, -v12
	v_fma_f32 v15, v249, v10, v13
	v_add_f32_e32 v10, v14, v16
	v_add_f32_e32 v11, v15, v17
	v_and_b32_e32 v16, 0xffff0000, v41
	v_and_b32_e32 v17, 0xffff0000, v45
	v_mul_f32_e32 v12, v249, v11
	v_mul_f32_e32 v13, v248, v11
	v_fma_f32 v14, v248, v10, -v12
	v_fma_f32 v15, v249, v10, v13
	v_add_f32_e32 v10, v14, v16
	v_add_f32_e32 v11, v15, v17
	v_lshlrev_b32_e32 v16, 16, v41
	v_lshlrev_b32_e32 v17, 16, v45
	v_mul_f32_e32 v12, v249, v11
	v_mul_f32_e32 v13, v248, v11
	v_fma_f32 v14, v248, v10, -v12
	v_fma_f32 v15, v249, v10, v13
	v_add_f32_e32 v10, v14, v16
	v_add_f32_e32 v11, v15, v17
	v_and_b32_e32 v16, 0xffff0000, v40
	v_and_b32_e32 v17, 0xffff0000, v44
	v_mul_f32_e32 v12, v249, v11
	v_mul_f32_e32 v13, v248, v11
	v_fma_f32 v14, v248, v10, -v12
	v_fma_f32 v15, v249, v10, v13
	v_add_f32_e32 v10, v14, v16
	v_add_f32_e32 v11, v15, v17
	v_lshlrev_b32_e32 v16, 16, v40
	v_lshlrev_b32_e32 v17, 16, v44
	v_mul_f32_e32 v12, v249, v11
	v_mul_f32_e32 v13, v248, v11
	v_fma_f32 v14, v248, v10, -v12
	v_fma_f32 v15, v249, v10, v13
	v_add_f32_e32 v10, v14, v16
	v_add_f32_e32 v11, v15, v17
	global_load_dwordx4 v[40:43], v30, s[10:11]
	global_load_dwordx4 v[44:47], v30, s[10:11] offset:1024
	s_sub_u32 s10, s10, 0x1000
	s_subb_u32 s11, s11, 0
	s_waitcnt vmcnt(6)
	v_and_b32_e32 v16, 0xffff0000, v51
	v_and_b32_e32 v17, 0xffff0000, v55
	v_mul_f32_e32 v12, v249, v11
	v_mul_f32_e32 v13, v248, v11
	v_fma_f32 v14, v248, v10, -v12
	v_fma_f32 v15, v249, v10, v13
	v_add_f32_e32 v10, v14, v16
	v_add_f32_e32 v11, v15, v17
	v_lshlrev_b32_e32 v16, 16, v51
	v_lshlrev_b32_e32 v17, 16, v55
	v_mul_f32_e32 v12, v249, v11
	v_mul_f32_e32 v13, v248, v11
	v_fma_f32 v14, v248, v10, -v12
	v_fma_f32 v15, v249, v10, v13
	v_add_f32_e32 v10, v14, v16
	v_add_f32_e32 v11, v15, v17
	v_and_b32_e32 v16, 0xffff0000, v50
	v_and_b32_e32 v17, 0xffff0000, v54
	v_mul_f32_e32 v12, v249, v11
	v_mul_f32_e32 v13, v248, v11
	v_fma_f32 v14, v248, v10, -v12
	v_fma_f32 v15, v249, v10, v13
	v_add_f32_e32 v10, v14, v16
	v_add_f32_e32 v11, v15, v17
	v_lshlrev_b32_e32 v16, 16, v50
	v_lshlrev_b32_e32 v17, 16, v54
	v_mul_f32_e32 v12, v249, v11
	v_mul_f32_e32 v13, v248, v11
	v_fma_f32 v14, v248, v10, -v12
	v_fma_f32 v15, v249, v10, v13
	v_add_f32_e32 v10, v14, v16
	v_add_f32_e32 v11, v15, v17
	v_and_b32_e32 v16, 0xffff0000, v49
	v_and_b32_e32 v17, 0xffff0000, v53
	v_mul_f32_e32 v12, v249, v11
	v_mul_f32_e32 v13, v248, v11
	v_fma_f32 v14, v248, v10, -v12
	v_fma_f32 v15, v249, v10, v13
	v_add_f32_e32 v10, v14, v16
	v_add_f32_e32 v11, v15, v17
	v_lshlrev_b32_e32 v16, 16, v49
	v_lshlrev_b32_e32 v17, 16, v53
	v_mul_f32_e32 v12, v249, v11
	v_mul_f32_e32 v13, v248, v11
	v_fma_f32 v14, v248, v10, -v12
	v_fma_f32 v15, v249, v10, v13
	v_add_f32_e32 v10, v14, v16
	v_add_f32_e32 v11, v15, v17
	v_and_b32_e32 v16, 0xffff0000, v48
	v_and_b32_e32 v17, 0xffff0000, v52
	v_mul_f32_e32 v12, v249, v11
	v_mul_f32_e32 v13, v248, v11
	v_fma_f32 v14, v248, v10, -v12
	v_fma_f32 v15, v249, v10, v13
	v_add_f32_e32 v10, v14, v16
	v_add_f32_e32 v11, v15, v17
	v_lshlrev_b32_e32 v16, 16, v48
	v_lshlrev_b32_e32 v17, 16, v52
	v_mul_f32_e32 v12, v249, v11
	v_mul_f32_e32 v13, v248, v11
	v_fma_f32 v14, v248, v10, -v12
	v_fma_f32 v15, v249, v10, v13
	v_add_f32_e32 v10, v14, v16
	v_add_f32_e32 v11, v15, v17
	global_load_dwordx4 v[48:51], v30, s[10:11]
	global_load_dwordx4 v[52:55], v30, s[10:11] offset:1024
	s_sub_u32 s10, s10, 0x1000
	s_subb_u32 s11, s11, 0
	s_waitcnt vmcnt(6)
; #define SCAN_STAMP(k) do { if (PROBE_SSM_PART == 3 + (k)) pt0 = __builtin_amdgcn_s_memrealtime(); if (PROBE_SSM_PART == 2 + (k)) pt1 = __builtin_amdgcn_s_memrealtime(); } while (0)
; __device__ __forceinline__ void scan_pair(Frame& F, const int g, const int b, unsigned long long& pt0, unsigned long long& pt1) {
;     ...
;     float qr = aTr, qi = aTi;
;     for (int k = 1; k < CPW; k <<= 1) { const float nr = qr * qr - qi * qi, ni = 2.f * qr * qi; qr = nr; qi = ni; }
;     __syncthreads();
;     ex[((r * 4 + wq) * 64 + n) * 2] = er; ex[((r * 4 + wq) * 64 + n) * 2 + 1] = ei;
;     __syncthreads();
;     SCAN_STAMP(2);
;     hr = h0r; hi = h0i;
;     for (int k = 0; k < wq; ++k) cmul_acc(hr, hi, qr, qi, ex[((r * 4 + k) * 64 + n) * 2], ex[((r * 4 + k) * 64 + n) * 2 + 1]);
	v_and_b32_e32 v16, 0xffff0000, v59
	v_and_b32_e32 v17, 0xffff0000, v63
	v_mul_f32_e32 v12, v249, v11
	v_mul_f32_e32 v13, v248, v11
	v_fma_f32 v14, v248, v10, -v12
	v_fma_f32 v15, v249, v10, v13
	v_add_f32_e32 v10, v14, v16
	v_add_f32_e32 v11, v15, v17
	v_lshlrev_b32_e32 v16, 16, v59
	v_lshlrev_b32_e32 v17, 16, v63
	v_mul_f32_e32 v12, v249, v11
	v_mul_f32_e32 v13, v248, v11
	v_fma_f32 v14, v248, v10, -v12
	v_fma_f32 v15, v249, v10, v13
	v_add_f32_e32 v10, v14, v16
	v_add_f32_e32 v11, v15, v17
	v_and_b32_e32 v16, 0xffff0000, v58
	v_and_b32_e32 v17, 0xffff0000, v62
	v_mul_f32_e32 v12, v249, v11
	v_mul_f32_e32 v13, v248, v11
	v_fma_f32 v14, v248, v10, -v12
	v_fma_f32 v15, v249, v10, v13
	v_add_f32_e32 v10, v14, v16
	v_add_f32_e32 v11, v15, v17
	v_lshlrev_b32_e32 v16, 16, v58
	v_lshlrev_b32_e32 v17, 16, v62
	v_mul_f32_e32 v12, v249, v11
	v_mul_f32_e32 v13, v248, v11
	v_fma_f32 v14, v248, v10, -v12
	v_fma_f32 v15, v249, v10, v13
	v_add_f32_e32 v10, v14, v16
	v_add_f32_e32 v11, v15, v17
	v_and_b32_e32 v16, 0xffff0000, v57
	v_and_b32_e32 v17, 0xffff0000, v61
	v_mul_f32_e32 v12, v249, v11
	v_mul_f32_e32 v13, v248, v11
	v_fma_f32 v14, v248, v10, -v12
	v_fma_f32 v15, v249, v10, v13
	v_add_f32_e32 v10, v14, v16
	v_add_f32_e32 v11, v15, v17
	v_lshlrev_b32_e32 v16, 16, v57
	v_lshlrev_b32_e32 v17, 16, v61
	v_mul_f32_e32 v12, v249, v11
	v_mul_f32_e32 v13, v248, v11
	v_fma_f32 v14, v248, v10, -v12
	v_fma_f32 v15, v249, v10, v13
	v_add_f32_e32 v10, v14, v16
	v_add_f32_e32 v11, v15, v17
	v_and_b32_e32 v16, 0xffff0000, v56
	v_and_b32_e32 v17, 0xffff0000, v60
	v_mul_f32_e32 v12, v249, v11
	v_mul_f32_e32 v13, v248, v11
	v_fma_f32 v14, v248, v10, -v12
	v_fma_f32 v15, v249, v10, v13
	v_add_f32_e32 v10, v14, v16
	v_add_f32_e32 v11, v15, v17
	v_lshlrev_b32_e32 v16, 16, v56
	v_lshlrev_b32_e32 v17, 16, v60
	v_mul_f32_e32 v12, v249, v11
	v_mul_f32_e32 v13, v248, v11
	v_fma_f32 v14, v248, v10, -v12
	v_fma_f32 v15, v249, v10, v13
	v_add_f32_e32 v10, v14, v16
	v_add_f32_e32 v11, v15, v17
	global_load_dwordx4 v[56:59], v30, s[10:11]
	global_load_dwordx4 v[60:63], v30, s[10:11] offset:1024
	s_sub_u32 s10, s10, 0x1000
	s_subb_u32 s11, s11, 0
	s_waitcnt vmcnt(6)
	v_and_b32_e32 v16, 0xffff0000, v67
	v_and_b32_e32 v17, 0xffff0000, v71
	v_mul_f32_e32 v12, v249, v11
	v_mul_f32_e32 v13, v248, v11
	v_fma_f32 v14, v248, v10, -v12
	v_fma_f32 v15, v249, v10, v13
	v_add_f32_e32 v10, v14, v16
	v_add_f32_e32 v11, v15, v17
	v_lshlrev_b32_e32 v16, 16, v67
	v_lshlrev_b32_e32 v17, 16, v71
	v_mul_f32_e32 v12, v249, v11
	v_mul_f32_e32 v13, v248, v11
	v_fma_f32 v14, v248, v10, -v12
	v_fma_f32 v15, v249, v10, v13
	v_add_f32_e32 v10, v14, v16
	v_add_f32_e32 v11, v15, v17
	v_and_b32_e32 v16, 0xffff0000, v66
	v_and_b32_e32 v17, 0xffff0000, v70
	v_mul_f32_e32 v12, v249, v11
	v_mul_f32_e32 v13, v248, v11
	v_fma_f32 v14, v248, v10, -v12
	v_fma_f32 v15, v249, v10, v13
	v_add_f32_e32 v10, v14, v16
	v_add_f32_e32 v11, v15, v17
	v_lshlrev_b32_e32 v16, 16, v66
	v_lshlrev_b32_e32 v17, 16, v70
	v_mul_f32_e32 v12, v249, v11
	v_mul_f32_e32 v13, v248, v11
	v_fma_f32 v14, v248, v10, -v12
	v_fma_f32 v15, v249, v10, v13
	v_add_f32_e32 v10, v14, v16
	v_add_f32_e32 v11, v15, v17
	v_and_b32_e32 v16, 0xffff0000, v65
	v_and_b32_e32 v17, 0xffff0000, v69
	v_mul_f32_e32 v12, v249, v11
	v_mul_f32_e32 v13, v248, v11
	v_fma_f32 v14, v248, v10, -v12
	v_fma_f32 v15, v249, v10, v13
	v_add_f32_e32 v10, v14, v16
	v_add_f32_e32 v11, v15, v17
	v_lshlrev_b32_e32 v16, 16, v65
	v_lshlrev_b32_e32 v17, 16, v69
	v_mul_f32_e32 v12, v249, v11
	v_mul_f32_e32 v13, v248, v11
	v_fma_f32 v14, v248, v10, -v12
	v_fma_f32 v15, v249, v10, v13
	v_add_f32_e32 v10, v14, v16
	v_add_f32_e32 v11, v15, v17
	v_and_b32_e32 v16, 0xffff0000, v64
	v_and_b32_e32 v17, 0xffff0000, v68
	v_mul_f32_e32 v12, v249, v11
	v_mul_f32_e32 v13, v248, v11
	v_fma_f32 v14, v248, v10, -v12
	v_fma_f32 v15, v249, v10, v13
	v_add_f32_e32 v10, v14, v16
	v_add_f32_e32 v11, v15, v17
	v_lshlrev_b32_e32 v16, 16, v64
	v_lshlrev_b32_e32 v17, 16, v68
	v_mul_f32_e32 v12, v249, v11
	v_mul_f32_e32 v13, v248, v11
	v_fma_f32 v14, v248, v10, -v12
	v_fma_f32 v15, v249, v10, v13
	v_add_f32_e32 v10, v14, v16
	v_add_f32_e32 v11, v15, v17
	global_load_dwordx4 v[64:67], v30, s[10:11]
	global_load_dwordx4 v[68:71], v30, s[10:11] offset:1024
	s_sub_u32 s10, s10, 0x1000
	s_subb_u32 s11, s11, 0
	s_sub_i32 s16, s16, 1
	s_cmp_lg_u32 s16, 0
	s_cbranch_scc1 .Lscl_p1r1
	s_waitcnt vmcnt(0)
.Lsc_mid:
	v_mov_b32_e32 v26, v10
	v_mov_b32_e32 v27, v11
	v_mov_b32_e32 v22, v248
	v_mov_b32_e32 v23, v249
	v_mul_f32_e32 v24, v23, v23
	v_add_f32_e32 v25, v22, v22
	v_fma_f32 v22, v22, v22, -v24
	v_mul_f32_e32 v23, v25, v23
	v_mul_f32_e32 v24, v23, v23
	v_add_f32_e32 v25, v22, v22
	v_fma_f32 v22, v22, v22, -v24
	v_mul_f32_e32 v23, v25, v23
	v_mul_f32_e32 v24, v23, v23
	v_add_f32_e32 v25, v22, v22
	v_fma_f32 v22, v22, v22, -v24
	v_mul_f32_e32 v23, v25, v23
	v_mul_f32_e32 v24, v23, v23
	v_add_f32_e32 v25, v22, v22
	v_fma_f32 v22, v22, v22, -v24
	v_mul_f32_e32 v23, v25, v23
	v_mul_f32_e32 v24, v23, v23
	v_add_f32_e32 v25, v22, v22
	v_fma_f32 v22, v22, v22, -v24
	v_mul_f32_e32 v23, v25, v23
	v_mul_f32_e32 v24, v23, v23
	v_add_f32_e32 v25, v22, v22
	v_fma_f32 v22, v22, v22, -v24
	v_mul_f32_e32 v23, v25, v23
	v_mul_f32_e32 v24, v23, v23
	v_add_f32_e32 v25, v22, v22
	v_fma_f32 v22, v22, v22, -v24
	v_mul_f32_e32 v23, v25, v23
	s_barrier
	ds_write_b64 v34, v[26:27]
	s_waitcnt lgkmcnt(0)
	s_barrier
	v_mov_b32_e32 v10, v20
	v_mov_b32_e32 v11, v21
	s_cmp_eq_u32 s6, 0
	s_cbranch_scc1 .Lsc_cmbd
	s_mov_b32 s16, s6
; #define GAS __attribute__((address_space(1)))
; #define LAS __attribute__((address_space(3)))
; #define SCAN_LOAD(HALF) do { _Pragma("unroll") for (int k = 0; k < 8; ++k) { const int kk = r ? (15 - 8 * (HALF) - k) : (8 * (HALF) + k); pre[k] = *(const u32x4*)(re_row + 2048 * kk); pim[k] = *(const u32x4*)(im_row + 2048 * kk); } } while (0)
; __device__ __forceinline__ void scan_pair(Frame& F, const int g, const int b, unsigned long long& pt0, unsigned long long& pt1) {
;     ...
;     hr = h0r; hi = h0i;
;     for (int k = 0; k < wq; ++k) cmul_acc(hr, hi, qr, qi, ex[((r * 4 + k) * 64 + n) * 2], ex[((r * 4 + k) * 64 + n) * 2 + 1]);
;     LAS bf16* tile = (LAS bf16*)(F.lds + 8192 + F.wave * 1024);
;     GAS char* hp = (GAS char*)(F.ws + WS_X + (size_t)g * XPLANE) + ((size_t)(TP / 64 + 2 * r + ((n & 15) >> 3)) * NCOL + (cb + (r ? CPW - 1 - (n >> 4) : (n >> 4)))) * 128 + (n & 7) * 16;
;     const long hstep4 = (r ? -4L : 4L) * 128;
; #pragma unroll
;     for (int half = 0; half < 2; ++half) { SCAN_LOAD(half);
;         if (r == 0) {
; #pragma unroll
;             for (int i = 0; i < 64; ++i) {
;                 ((LAS unsigned*)tile)[(i & 3) * 64 + n] = pk2(hr, hi);
;                 if ((i & 3) == 3) { const u32x4 w = *(const LAS u32x4*)((const LAS char*)tile + n * 16); *(GAS u32x4*)hp = w; hp += hstep4; asm volatile("" : "+v"(hp)); }
;                 cmul_acc(hr, hi, aTr, aTi, bf2f(pre[i >> 3][(i & 7) >> 1] >> (16 * (i & 1))), bf2f(pim[i >> 3][(i & 7) >> 1] >> (16 * (i & 1)))); }
.Lsc_cmb:
	ds_read_b64 v[96:97], v35
	v_add_u32_e32 v35, 0x200, v35
	v_mul_f32_e32 v12, v23, v11
	v_mul_f32_e32 v13, v22, v11
	v_fma_f32 v14, v22, v10, -v12
	v_fma_f32 v15, v23, v10, v13
	s_waitcnt lgkmcnt(0)
	v_add_f32_e32 v10, v14, v96
	v_add_f32_e32 v11, v15, v97
	s_sub_i32 s16, s16, 1
	s_cmp_lg_u32 s16, 0
	s_cbranch_scc1 .Lsc_cmb
.Lsc_cmbd:
	s_cmp_lg_u32 s5, 0
	s_cbranch_scc1 .Lsc_p2r1
	s_mov_b64 s[10:11], s[68:69]
	global_load_dwordx4 v[40:43], v30, s[10:11]
	global_load_dwordx4 v[44:47], v30, s[10:11] offset:1024
	s_add_u32 s10, s10, 0x1000
	s_addc_u32 s11, s11, 0
	global_load_dwordx4 v[48:51], v30, s[10:11]
	global_load_dwordx4 v[52:55], v30, s[10:11] offset:1024
	s_add_u32 s10, s10, 0x1000
	s_addc_u32 s11, s11, 0
	global_load_dwordx4 v[56:59], v30, s[10:11]
	global_load_dwordx4 v[60:63], v30, s[10:11] offset:1024
	s_add_u32 s10, s10, 0x1000
	s_addc_u32 s11, s11, 0
	global_load_dwordx4 v[64:67], v30, s[10:11]
	global_load_dwordx4 v[68:71], v30, s[10:11] offset:1024
	s_add_u32 s10, s10, 0x1000
	s_addc_u32 s11, s11, 0
	s_waitcnt vmcnt(0)
	s_mov_b32 s16, 4
.Lscl_p2r0:
	s_waitcnt vmcnt(12)
	v_cvt_pk_bf16_f32 v76, v10, v11
	ds_write_b32 v32, v76
	v_lshlrev_b32_e32 v16, 16, v40
	v_lshlrev_b32_e32 v17, 16, v44
	v_mul_f32_e32 v12, v249, v11
	v_mul_f32_e32 v13, v248, v11
	v_fma_f32 v14, v248, v10, -v12
	v_fma_f32 v15, v249, v10, v13
	v_add_f32_e32 v10, v14, v16
	v_add_f32_e32 v11, v15, v17
	v_cvt_pk_bf16_f32 v76, v10, v11
	ds_write_b32 v32, v76 offset:256
	v_and_b32_e32 v16, 0xffff0000, v40
	v_and_b32_e32 v17, 0xffff0000, v44
	v_mul_f32_e32 v12, v249, v11
	v_mul_f32_e32 v13, v248, v11
	v_fma_f32 v14, v248, v10, -v12
	v_fma_f32 v15, v249, v10, v13
	v_add_f32_e32 v10, v14, v16
	v_add_f32_e32 v11, v15, v17
	v_cvt_pk_bf16_f32 v76, v10, v11
	ds_write_b32 v32, v76 offset:512
	v_lshlrev_b32_e32 v16, 16, v41
	v_lshlrev_b32_e32 v17, 16, v45
	v_mul_f32_e32 v12, v249, v11
	v_mul_f32_e32 v13, v248, v11
	v_fma_f32 v14, v248, v10, -v12
	v_fma_f32 v15, v249, v10, v13
	v_add_f32_e32 v10, v14, v16
	v_add_f32_e32 v11, v15, v17
	v_cvt_pk_bf16_f32 v76, v10, v11
	ds_write_b32 v32, v76 offset:768
	ds_read_b128 v[72:75], v33
	v_and_b32_e32 v16, 0xffff0000, v41
	v_and_b32_e32 v17, 0xffff0000, v45
	v_mul_f32_e32 v12, v249, v11
	v_mul_f32_e32 v13, v248, v11
	v_fma_f32 v14, v248, v10, -v12
	v_fma_f32 v15, v249, v10, v13
	v_add_f32_e32 v10, v14, v16
	v_add_f32_e32 v11, v15, v17
	s_waitcnt lgkmcnt(0)
	global_store_dwordx4 v31, v[72:75], s[28:29]
	s_add_u32 s28, s28, 0x200
	s_addc_u32 s29, s29, 0
	v_cvt_pk_bf16_f32 v76, v10, v11
	ds_write_b32 v32, v76
	v_lshlrev_b32_e32 v16, 16, v42
	v_lshlrev_b32_e32 v17, 16, v46
	v_mul_f32_e32 v12, v249, v11
	v_mul_f32_e32 v13, v248, v11
	v_fma_f32 v14, v248, v10, -v12
	v_fma_f32 v15, v249, v10, v13
	v_add_f32_e32 v10, v14, v16
	v_add_f32_e32 v11, v15, v17
	v_cvt_pk_bf16_f32 v76, v10, v11
	ds_write_b32 v32, v76 offset:256
	v_and_b32_e32 v16, 0xffff0000, v42
	v_and_b32_e32 v17, 0xffff0000, v46
	v_mul_f32_e32 v12, v249, v11
	v_mul_f32_e32 v13, v248, v11
	v_fma_f32 v14, v248, v10, -v12
	v_fma_f32 v15, v249, v10, v13
	v_add_f32_e32 v10, v14, v16
	v_add_f32_e32 v11, v15, v17
	v_cvt_pk_bf16_f32 v76, v10, v11
	ds_write_b32 v32, v76 offset:512
	v_lshlrev_b32_e32 v16, 16, v43
	v_lshlrev_b32_e32 v17, 16, v47
	v_mul_f32_e32 v12, v249, v11
	v_mul_f32_e32 v13, v248, v11
	v_fma_f32 v14, v248, v10, -v12
	v_fma_f32 v15, v249, v10, v13
	v_add_f32_e32 v10, v14, v16
	v_add_f32_e32 v11, v15, v17
	v_cvt_pk_bf16_f32 v76, v10, v11
	ds_write_b32 v32, v76 offset:768
	ds_read_b128 v[72:75], v33
	v_and_b32_e32 v16, 0xffff0000, v43
	v_and_b32_e32 v17, 0xffff0000, v47
	v_mul_f32_e32 v12, v249, v11
	v_mul_f32_e32 v13, v248, v11
	v_fma_f32 v14, v248, v10, -v12
	v_fma_f32 v15, v249, v10, v13
	v_add_f32_e32 v10, v14, v16
	v_add_f32_e32 v11, v15, v17
	s_waitcnt lgkmcnt(0)
	global_store_dwordx4 v31, v[72:75], s[28:29]
	s_add_u32 s28, s28, 0x200
	s_addc_u32 s29, s29, 0
	global_load_dwordx4 v[40:43], v30, s[10:11]
	global_load_dwordx4 v[44:47], v30, s[10:11] offset:1024
	s_add_u32 s10, s10, 0x1000
	s_addc_u32 s11, s11, 0
	s_waitcnt vmcnt(12)
	v_cvt_pk_bf16_f32 v76, v10, v11
	ds_write_b32 v32, v76
	v_lshlrev_b32_e32 v16, 16, v48
	v_lshlrev_b32_e32 v17, 16, v52
	v_mul_f32_e32 v12, v249, v11
	v_mul_f32_e32 v13, v248, v11
	v_fma_f32 v14, v248, v10, -v12
	v_fma_f32 v15, v249, v10, v13
	v_add_f32_e32 v10, v14, v16
	v_add_f32_e32 v11, v15, v17
	v_cvt_pk_bf16_f32 v76, v10, v11
	ds_write_b32 v32, v76 offset:256
	v_and_b32_e32 v16, 0xffff0000, v48
	v_and_b32_e32 v17, 0xffff0000, v52
	v_mul_f32_e32 v12, v249, v11
	v_mul_f32_e32 v13, v248, v11
	v_fma_f32 v14, v248, v10, -v12
	v_fma_f32 v15, v249, v10, v13
	v_add_f32_e32 v10, v14, v16
	v_add_f32_e32 v11, v15, v17
	v_cvt_pk_bf16_f32 v76, v10, v11
	ds_write_b32 v32, v76 offset:512
	v_lshlrev_b32_e32 v16, 16, v49
	v_lshlrev_b32_e32 v17, 16, v53
	v_mul_f32_e32 v12, v249, v11
	v_mul_f32_e32 v13, v248, v11
	v_fma_f32 v14, v248, v10, -v12
	v_fma_f32 v15, v249, v10, v13
	v_add_f32_e32 v10, v14, v16
	v_add_f32_e32 v11, v15, v17
	v_cvt_pk_bf16_f32 v76, v10, v11
	ds_write_b32 v32, v76 offset:768
	ds_read_b128 v[72:75], v33
	v_and_b32_e32 v16, 0xffff0000, v49
	v_and_b32_e32 v17, 0xffff0000, v53
	v_mul_f32_e32 v12, v249, v11
	v_mul_f32_e32 v13, v248, v11
	v_fma_f32 v14, v248, v10, -v12
	v_fma_f32 v15, v249, v10, v13
	v_add_f32_e32 v10, v14, v16
	v_add_f32_e32 v11, v15, v17
	s_waitcnt lgkmcnt(0)
; #define GAS __attribute__((address_space(1)))
; #define LAS __attribute__((address_space(3)))
; #define SCAN_LOAD(HALF) do { _Pragma("unroll") for (int k = 0; k < 8; ++k) { const int kk = r ? (15 - 8 * (HALF) - k) : (8 * (HALF) + k); pre[k] = *(const u32x4*)(re_row + 2048 * kk); pim[k] = *(const u32x4*)(im_row + 2048 * kk); } } while (0)
; __device__ __forceinline__ void scan_pair(Frame& F, const int g, const int b, unsigned long long& pt0, unsigned long long& pt1) {
;     ...
;     for (int half = 0; half < 2; ++half) { SCAN_LOAD(half);
;         if (r == 0) {
; #pragma unroll
;             for (int i = 0; i < 64; ++i) {
;                 ((LAS unsigned*)tile)[(i & 3) * 64 + n] = pk2(hr, hi);
;                 if ((i & 3) == 3) { const u32x4 w = *(const LAS u32x4*)((const LAS char*)tile + n * 16); *(GAS u32x4*)hp = w; hp += hstep4; asm volatile("" : "+v"(hp)); }
;                 cmul_acc(hr, hi, aTr, aTi, bf2f(pre[i >> 3][(i & 7) >> 1] >> (16 * (i & 1))), bf2f(pim[i >> 3][(i & 7) >> 1] >> (16 * (i & 1)))); }
	global_store_dwordx4 v31, v[72:75], s[28:29]
	s_add_u32 s28, s28, 0x200
	s_addc_u32 s29, s29, 0
	v_cvt_pk_bf16_f32 v76, v10, v11
	ds_write_b32 v32, v76
	v_lshlrev_b32_e32 v16, 16, v50
	v_lshlrev_b32_e32 v17, 16, v54
	v_mul_f32_e32 v12, v249, v11
	v_mul_f32_e32 v13, v248, v11
	v_fma_f32 v14, v248, v10, -v12
	v_fma_f32 v15, v249, v10, v13
	v_add_f32_e32 v10, v14, v16
	v_add_f32_e32 v11, v15, v17
	v_cvt_pk_bf16_f32 v76, v10, v11
	ds_write_b32 v32, v76 offset:256
	v_and_b32_e32 v16, 0xffff0000, v50
	v_and_b32_e32 v17, 0xffff0000, v54
	v_mul_f32_e32 v12, v249, v11
	v_mul_f32_e32 v13, v248, v11
	v_fma_f32 v14, v248, v10, -v12
	v_fma_f32 v15, v249, v10, v13
	v_add_f32_e32 v10, v14, v16
	v_add_f32_e32 v11, v15, v17
	v_cvt_pk_bf16_f32 v76, v10, v11
	ds_write_b32 v32, v76 offset:512
	v_lshlrev_b32_e32 v16, 16, v51
	v_lshlrev_b32_e32 v17, 16, v55
	v_mul_f32_e32 v12, v249, v11
	v_mul_f32_e32 v13, v248, v11
	v_fma_f32 v14, v248, v10, -v12
	v_fma_f32 v15, v249, v10, v13
	v_add_f32_e32 v10, v14, v16
	v_add_f32_e32 v11, v15, v17
	v_cvt_pk_bf16_f32 v76, v10, v11
	ds_write_b32 v32, v76 offset:768
	ds_read_b128 v[72:75], v33
	v_and_b32_e32 v16, 0xffff0000, v51
	v_and_b32_e32 v17, 0xffff0000, v55
	v_mul_f32_e32 v12, v249, v11
	v_mul_f32_e32 v13, v248, v11
	v_fma_f32 v14, v248, v10, -v12
	v_fma_f32 v15, v249, v10, v13
	v_add_f32_e32 v10, v14, v16
	v_add_f32_e32 v11, v15, v17
	s_waitcnt lgkmcnt(0)
	global_store_dwordx4 v31, v[72:75], s[28:29]
	s_add_u32 s28, s28, 0x200
	s_addc_u32 s29, s29, 0
	global_load_dwordx4 v[48:51], v30, s[10:11]
	global_load_dwordx4 v[52:55], v30, s[10:11] offset:1024
	s_add_u32 s10, s10, 0x1000
	s_addc_u32 s11, s11, 0
	s_waitcnt vmcnt(12)
	v_cvt_pk_bf16_f32 v76, v10, v11
	ds_write_b32 v32, v76
	v_lshlrev_b32_e32 v16, 16, v56
	v_lshlrev_b32_e32 v17, 16, v60
	v_mul_f32_e32 v12, v249, v11
	v_mul_f32_e32 v13, v248, v11
	v_fma_f32 v14, v248, v10, -v12
	v_fma_f32 v15, v249, v10, v13
	v_add_f32_e32 v10, v14, v16
	v_add_f32_e32 v11, v15, v17
	v_cvt_pk_bf16_f32 v76, v10, v11
	ds_write_b32 v32, v76 offset:256
	v_and_b32_e32 v16, 0xffff0000, v56
	v_and_b32_e32 v17, 0xffff0000, v60
	v_mul_f32_e32 v12, v249, v11
	v_mul_f32_e32 v13, v248, v11
	v_fma_f32 v14, v248, v10, -v12
	v_fma_f32 v15, v249, v10, v13
	v_add_f32_e32 v10, v14, v16
	v_add_f32_e32 v11, v15, v17
	v_cvt_pk_bf16_f32 v76, v10, v11
	ds_write_b32 v32, v76 offset:512
	v_lshlrev_b32_e32 v16, 16, v57
	v_lshlrev_b32_e32 v17, 16, v61
	v_mul_f32_e32 v12, v249, v11
	v_mul_f32_e32 v13, v248, v11
	v_fma_f32 v14, v248, v10, -v12
	v_fma_f32 v15, v249, v10, v13
	v_add_f32_e32 v10, v14, v16
	v_add_f32_e32 v11, v15, v17
	v_cvt_pk_bf16_f32 v76, v10, v11
	ds_write_b32 v32, v76 offset:768
	ds_read_b128 v[72:75], v33
	v_and_b32_e32 v16, 0xffff0000, v57
	v_and_b32_e32 v17, 0xffff0000, v61
	v_mul_f32_e32 v12, v249, v11
	v_mul_f32_e32 v13, v248, v11
	v_fma_f32 v14, v248, v10, -v12
	v_fma_f32 v15, v249, v10, v13
	v_add_f32_e32 v10, v14, v16
	v_add_f32_e32 v11, v15, v17
	s_waitcnt lgkmcnt(0)
	global_store_dwordx4 v31, v[72:75], s[28:29]
	s_add_u32 s28, s28, 0x200
	s_addc_u32 s29, s29, 0
	v_cvt_pk_bf16_f32 v76, v10, v11
	ds_write_b32 v32, v76
	v_lshlrev_b32_e32 v16, 16, v58
	v_lshlrev_b32_e32 v17, 16, v62
	v_mul_f32_e32 v12, v249, v11
	v_mul_f32_e32 v13, v248, v11
	v_fma_f32 v14, v248, v10, -v12
	v_fma_f32 v15, v249, v10, v13
	v_add_f32_e32 v10, v14, v16
	v_add_f32_e32 v11, v15, v17
	v_cvt_pk_bf16_f32 v76, v10, v11
	ds_write_b32 v32, v76 offset:256
	v_and_b32_e32 v16, 0xffff0000, v58
	v_and_b32_e32 v17, 0xffff0000, v62
	v_mul_f32_e32 v12, v249, v11
	v_mul_f32_e32 v13, v248, v11
	v_fma_f32 v14, v248, v10, -v12
	v_fma_f32 v15, v249, v10, v13
	v_add_f32_e32 v10, v14, v16
	v_add_f32_e32 v11, v15, v17
	v_cvt_pk_bf16_f32 v76, v10, v11
	ds_write_b32 v32, v76 offset:512
	v_lshlrev_b32_e32 v16, 16, v59
	v_lshlrev_b32_e32 v17, 16, v63
	v_mul_f32_e32 v12, v249, v11
	v_mul_f32_e32 v13, v248, v11
	v_fma_f32 v14, v248, v10, -v12
	v_fma_f32 v15, v249, v10, v13
	v_add_f32_e32 v10, v14, v16
	v_add_f32_e32 v11, v15, v17
	v_cvt_pk_bf16_f32 v76, v10, v11
	ds_write_b32 v32, v76 offset:768
	ds_read_b128 v[72:75], v33
	v_and_b32_e32 v16, 0xffff0000, v59
	v_and_b32_e32 v17, 0xffff0000, v63
	v_mul_f32_e32 v12, v249, v11
	v_mul_f32_e32 v13, v248, v11
	v_fma_f32 v14, v248, v10, -v12
	v_fma_f32 v15, v249, v10, v13
	v_add_f32_e32 v10, v14, v16
	v_add_f32_e32 v11, v15, v17
	s_waitcnt lgkmcnt(0)
; #define GAS __attribute__((address_space(1)))
; #define LAS __attribute__((address_space(3)))
; #define SCAN_LOAD(HALF) do { _Pragma("unroll") for (int k = 0; k < 8; ++k) { const int kk = r ? (15 - 8 * (HALF) - k) : (8 * (HALF) + k); pre[k] = *(const u32x4*)(re_row + 2048 * kk); pim[k] = *(const u32x4*)(im_row + 2048 * kk); } } while (0)
; __device__ __forceinline__ void scan_pair(Frame& F, const int g, const int b, unsigned long long& pt0, unsigned long long& pt1) {
;     ...
;     for (int half = 0; half < 2; ++half) { SCAN_LOAD(half);
;         if (r == 0) {
; #pragma unroll
;             for (int i = 0; i < 64; ++i) {
;                 ((LAS unsigned*)tile)[(i & 3) * 64 + n] = pk2(hr, hi);
;                 if ((i & 3) == 3) { const u32x4 w = *(const LAS u32x4*)((const LAS char*)tile + n * 16); *(GAS u32x4*)hp = w; hp += hstep4; asm volatile("" : "+v"(hp)); }
;                 cmul_acc(hr, hi, aTr, aTi, bf2f(pre[i >> 3][(i & 7) >> 1] >> (16 * (i & 1))), bf2f(pim[i >> 3][(i & 7) >> 1] >> (16 * (i & 1)))); }
	global_store_dwordx4 v31, v[72:75], s[28:29]
	s_add_u32 s28, s28, 0x200
	s_addc_u32 s29, s29, 0
	global_load_dwordx4 v[56:59], v30, s[10:11]
	global_load_dwordx4 v[60:63], v30, s[10:11] offset:1024
	s_add_u32 s10, s10, 0x1000
	s_addc_u32 s11, s11, 0
	s_waitcnt vmcnt(12)
	v_cvt_pk_bf16_f32 v76, v10, v11
	ds_write_b32 v32, v76
	v_lshlrev_b32_e32 v16, 16, v64
	v_lshlrev_b32_e32 v17, 16, v68
	v_mul_f32_e32 v12, v249, v11
	v_mul_f32_e32 v13, v248, v11
	v_fma_f32 v14, v248, v10, -v12
	v_fma_f32 v15, v249, v10, v13
	v_add_f32_e32 v10, v14, v16
	v_add_f32_e32 v11, v15, v17
	v_cvt_pk_bf16_f32 v76, v10, v11
	ds_write_b32 v32, v76 offset:256
	v_and_b32_e32 v16, 0xffff0000, v64
	v_and_b32_e32 v17, 0xffff0000, v68
	v_mul_f32_e32 v12, v249, v11
	v_mul_f32_e32 v13, v248, v11
	v_fma_f32 v14, v248, v10, -v12
	v_fma_f32 v15, v249, v10, v13
	v_add_f32_e32 v10, v14, v16
	v_add_f32_e32 v11, v15, v17
	v_cvt_pk_bf16_f32 v76, v10, v11
	ds_write_b32 v32, v76 offset:512
	v_lshlrev_b32_e32 v16, 16, v65
	v_lshlrev_b32_e32 v17, 16, v69
	v_mul_f32_e32 v12, v249, v11
	v_mul_f32_e32 v13, v248, v11
	v_fma_f32 v14, v248, v10, -v12
	v_fma_f32 v15, v249, v10, v13
	v_add_f32_e32 v10, v14, v16
	v_add_f32_e32 v11, v15, v17
	v_cvt_pk_bf16_f32 v76, v10, v11
	ds_write_b32 v32, v76 offset:768
	ds_read_b128 v[72:75], v33
	v_and_b32_e32 v16, 0xffff0000, v65
	v_and_b32_e32 v17, 0xffff0000, v69
	v_mul_f32_e32 v12, v249, v11
	v_mul_f32_e32 v13, v248, v11
	v_fma_f32 v14, v248, v10, -v12
	v_fma_f32 v15, v249, v10, v13
	v_add_f32_e32 v10, v14, v16
	v_add_f32_e32 v11, v15, v17
	s_waitcnt lgkmcnt(0)
	global_store_dwordx4 v31, v[72:75], s[28:29]
	s_add_u32 s28, s28, 0x200
	s_addc_u32 s29, s29, 0
	v_cvt_pk_bf16_f32 v76, v10, v11
	ds_write_b32 v32, v76
	v_lshlrev_b32_e32 v16, 16, v66
	v_lshlrev_b32_e32 v17, 16, v70
	v_mul_f32_e32 v12, v249, v11
	v_mul_f32_e32 v13, v248, v11
	v_fma_f32 v14, v248, v10, -v12
	v_fma_f32 v15, v249, v10, v13
	v_add_f32_e32 v10, v14, v16
	v_add_f32_e32 v11, v15, v17
	v_cvt_pk_bf16_f32 v76, v10, v11
	ds_write_b32 v32, v76 offset:256
	v_and_b32_e32 v16, 0xffff0000, v66
	v_and_b32_e32 v17, 0xffff0000, v70
	v_mul_f32_e32 v12, v249, v11
	v_mul_f32_e32 v13, v248, v11
	v_fma_f32 v14, v248, v10, -v12
	v_fma_f32 v15, v249, v10, v13
	v_add_f32_e32 v10, v14, v16
	v_add_f32_e32 v11, v15, v17
	v_cvt_pk_bf16_f32 v76, v10, v11
	ds_write_b32 v32, v76 offset:512
	v_lshlrev_b32_e32 v16, 16, v67
	v_lshlrev_b32_e32 v17, 16, v71
	v_mul_f32_e32 v12, v249, v11
	v_mul_f32_e32 v13, v248, v11
	v_fma_f32 v14, v248, v10, -v12
	v_fma_f32 v15, v249, v10, v13
	v_add_f32_e32 v10, v14, v16
	v_add_f32_e32 v11, v15, v17
	v_cvt_pk_bf16_f32 v76, v10, v11
	ds_write_b32 v32, v76 offset:768
	ds_read_b128 v[72:75], v33
	v_and_b32_e32 v16, 0xffff0000, v67
	v_and_b32_e32 v17, 0xffff0000, v71
	v_mul_f32_e32 v12, v249, v11
	v_mul_f32_e32 v13, v248, v11
	v_fma_f32 v14, v248, v10, -v12
	v_fma_f32 v15, v249, v10, v13
	v_add_f32_e32 v10, v14, v16
	v_add_f32_e32 v11, v15, v17
	s_waitcnt lgkmcnt(0)
	global_store_dwordx4 v31, v[72:75], s[28:29]
	s_add_u32 s28, s28, 0x200
	s_addc_u32 s29, s29, 0
	global_load_dwordx4 v[64:67], v30, s[10:11]
	global_load_dwordx4 v[68:71], v30, s[10:11] offset:1024
	s_add_u32 s10, s10, 0x1000
	s_addc_u32 s11, s11, 0
	s_sub_i32 s16, s16, 1
	s_cmp_lg_u32 s16, 0
	s_cbranch_scc1 .Lscl_p2r0
	s_waitcnt vmcnt(0)
	s_branch .Lsc_end

; #define GAS __attribute__((address_space(1)))
; #define LAS __attribute__((address_space(3)))
; __device__ __forceinline__ void scan_pair(Frame& F, const int g, const int b, unsigned long long& pt0, unsigned long long& pt1) {
;     ...
;         } else {
; #pragma unroll
;             for (int i = 0; i < 64; ++i) { const int e = 7 - (i & 7);
;                 ((LAS unsigned*)tile)[(i & 3) * 64 + n] = pk2(hr, hi);
;                 if ((i & 3) == 3) { const u32x4 w = *(const LAS u32x4*)((const LAS char*)tile + n * 16); *(GAS u32x4*)hp = w; hp += hstep4; asm volatile("" : "+v"(hp)); }
;                 cmul_acc(hr, hi, aTr, aTi, bf2f(pre[i >> 3][e >> 1] >> (16 * (e & 1))), bf2f(pim[i >> 3][e >> 1] >> (16 * (e & 1)))); }
;         }
;         asm volatile("" ::: "memory"); }
.Lscl_p2r1:
	s_waitcnt vmcnt(12)
	v_cvt_pk_bf16_f32 v76, v10, v11
	ds_write_b32 v32, v76
	v_and_b32_e32 v16, 0xffff0000, v43
	v_and_b32_e32 v17, 0xffff0000, v47
	v_mul_f32_e32 v12, v249, v11
	v_mul_f32_e32 v13, v248, v11
	v_fma_f32 v14, v248, v10, -v12
	v_fma_f32 v15, v249, v10, v13
	v_add_f32_e32 v10, v14, v16
	v_add_f32_e32 v11, v15, v17
	v_cvt_pk_bf16_f32 v76, v10, v11
	ds_write_b32 v32, v76 offset:256
	v_lshlrev_b32_e32 v16, 16, v43
	v_lshlrev_b32_e32 v17, 16, v47
	v_mul_f32_e32 v12, v249, v11
	v_mul_f32_e32 v13, v248, v11
	v_fma_f32 v14, v248, v10, -v12
	v_fma_f32 v15, v249, v10, v13
	v_add_f32_e32 v10, v14, v16
	v_add_f32_e32 v11, v15, v17
	v_cvt_pk_bf16_f32 v76, v10, v11
	ds_write_b32 v32, v76 offset:512
	v_and_b32_e32 v16, 0xffff0000, v42
	v_and_b32_e32 v17, 0xffff0000, v46
	v_mul_f32_e32 v12, v249, v11
	v_mul_f32_e32 v13, v248, v11
	v_fma_f32 v14, v248, v10, -v12
	v_fma_f32 v15, v249, v10, v13
	v_add_f32_e32 v10, v14, v16
	v_add_f32_e32 v11, v15, v17
	v_cvt_pk_bf16_f32 v76, v10, v11
	ds_write_b32 v32, v76 offset:768
	ds_read_b128 v[72:75], v33
	v_lshlrev_b32_e32 v16, 16, v42
	v_lshlrev_b32_e32 v17, 16, v46
	v_mul_f32_e32 v12, v249, v11
	v_mul_f32_e32 v13, v248, v11
	v_fma_f32 v14, v248, v10, -v12
	v_fma_f32 v15, v249, v10, v13
	v_add_f32_e32 v10, v14, v16
	v_add_f32_e32 v11, v15, v17
	s_waitcnt lgkmcnt(0)
	global_store_dwordx4 v31, v[72:75], s[28:29]
	s_sub_u32 s28, s28, 0x200
	s_subb_u32 s29, s29, 0
	v_cvt_pk_bf16_f32 v76, v10, v11
	ds_write_b32 v32, v76
	v_and_b32_e32 v16, 0xffff0000, v41
	v_and_b32_e32 v17, 0xffff0000, v45
	v_mul_f32_e32 v12, v249, v11
	v_mul_f32_e32 v13, v248, v11
	v_fma_f32 v14, v248, v10, -v12
	v_fma_f32 v15, v249, v10, v13
	v_add_f32_e32 v10, v14, v16
	v_add_f32_e32 v11, v15, v17
	v_cvt_pk_bf16_f32 v76, v10, v11
	ds_write_b32 v32, v76 offset:256
	v_lshlrev_b32_e32 v16, 16, v41
	v_lshlrev_b32_e32 v17, 16, v45
	v_mul_f32_e32 v12, v249, v11
	v_mul_f32_e32 v13, v248, v11
	v_fma_f32 v14, v248, v10, -v12
	v_fma_f32 v15, v249, v10, v13
	v_add_f32_e32 v10, v14, v16
	v_add_f32_e32 v11, v15, v17
	v_cvt_pk_bf16_f32 v76, v10, v11
	ds_write_b32 v32, v76 offset:512
	v_and_b32_e32 v16, 0xffff0000, v40
	v_and_b32_e32 v17, 0xffff0000, v44
	v_mul_f32_e32 v12, v249, v11
	v_mul_f32_e32 v13, v248, v11
	v_fma_f32 v14, v248, v10, -v12
	v_fma_f32 v15, v249, v10, v13
	v_add_f32_e32 v10, v14, v16
	v_add_f32_e32 v11, v15, v17
	v_cvt_pk_bf16_f32 v76, v10, v11
	ds_write_b32 v32, v76 offset:768
	ds_read_b128 v[72:75], v33
	v_lshlrev_b32_e32 v16, 16, v40
	v_lshlrev_b32_e32 v17, 16, v44
	v_mul_f32_e32 v12, v249, v11
	v_mul_f32_e32 v13, v248, v11
	v_fma_f32 v14, v248, v10, -v12
	v_fma_f32 v15, v249, v10, v13
	v_add_f32_e32 v10, v14, v16
	v_add_f32_e32 v11, v15, v17
	s_waitcnt lgkmcnt(0)
	global_store_dwordx4 v31, v[72:75], s[28:29]
	s_sub_u32 s28, s28, 0x200
	s_subb_u32 s29, s29, 0
	global_load_dwordx4 v[40:43], v30, s[10:11]
	global_load_dwordx4 v[44:47], v30, s[10:11] offset:1024
	s_sub_u32 s10, s10, 0x1000
	s_subb_u32 s11, s11, 0
	s_waitcnt vmcnt(12)
	v_cvt_pk_bf16_f32 v76, v10, v11
	ds_write_b32 v32, v76
	v_and_b32_e32 v16, 0xffff0000, v51
	v_and_b32_e32 v17, 0xffff0000, v55
	v_mul_f32_e32 v12, v249, v11
	v_mul_f32_e32 v13, v248, v11
	v_fma_f32 v14, v248, v10, -v12
	v_fma_f32 v15, v249, v10, v13
	v_add_f32_e32 v10, v14, v16
	v_add_f32_e32 v11, v15, v17
	v_cvt_pk_bf16_f32 v76, v10, v11
	ds_write_b32 v32, v76 offset:256
	v_lshlrev_b32_e32 v16, 16, v51
	v_lshlrev_b32_e32 v17, 16, v55
	v_mul_f32_e32 v12, v249, v11
	v_mul_f32_e32 v13, v248, v11
	v_fma_f32 v14, v248, v10, -v12
	v_fma_f32 v15, v249, v10, v13
	v_add_f32_e32 v10, v14, v16
	v_add_f32_e32 v11, v15, v17
	v_cvt_pk_bf16_f32 v76, v10, v11
	ds_write_b32 v32, v76 offset:512
	v_and_b32_e32 v16, 0xffff0000, v50
	v_and_b32_e32 v17, 0xffff0000, v54
	v_mul_f32_e32 v12, v249, v11
	v_mul_f32_e32 v13, v248, v11
	v_fma_f32 v14, v248, v10, -v12
	v_fma_f32 v15, v249, v10, v13
	v_add_f32_e32 v10, v14, v16
	v_add_f32_e32 v11, v15, v17
	v_cvt_pk_bf16_f32 v76, v10, v11
	ds_write_b32 v32, v76 offset:768
	ds_read_b128 v[72:75], v33
	v_lshlrev_b32_e32 v16, 16, v50
	v_lshlrev_b32_e32 v17, 16, v54
	v_mul_f32_e32 v12, v249, v11
	v_mul_f32_e32 v13, v248, v11
	v_fma_f32 v14, v248, v10, -v12
	v_fma_f32 v15, v249, v10, v13
	v_add_f32_e32 v10, v14, v16
	v_add_f32_e32 v11, v15, v17
	s_waitcnt lgkmcnt(0)
	global_store_dwordx4 v31, v[72:75], s[28:29]
	s_sub_u32 s28, s28, 0x200
	s_subb_u32 s29, s29, 0
	v_cvt_pk_bf16_f32 v76, v10, v11
	ds_write_b32 v32, v76
	v_and_b32_e32 v16, 0xffff0000, v49
	v_and_b32_e32 v17, 0xffff0000, v53
	v_mul_f32_e32 v12, v249, v11
	v_mul_f32_e32 v13, v248, v11
	v_fma_f32 v14, v248, v10, -v12
	v_fma_f32 v15, v249, v10, v13
	v_add_f32_e32 v10, v14, v16
	v_add_f32_e32 v11, v15, v17
	v_cvt_pk_bf16_f32 v76, v10, v11
	ds_write_b32 v32, v76 offset:256
	v_lshlrev_b32_e32 v16, 16, v49
	v_lshlrev_b32_e32 v17, 16, v53
	v_mul_f32_e32 v12, v249, v11
	v_mul_f32_e32 v13, v248, v11
	v_fma_f32 v14, v248, v10, -v12
	v_fma_f32 v15, v249, v10, v13
	v_add_f32_e32 v10, v14, v16
	v_add_f32_e32 v11, v15, v17
	v_cvt_pk_bf16_f32 v76, v10, v11
	ds_write_b32 v32, v76 offset:512
	v_and_b32_e32 v16, 0xffff0000, v48
	v_and_b32_e32 v17, 0xffff0000, v52
	v_mul_f32_e32 v12, v249, v11
	v_mul_f32_e32 v13, v248, v11
	v_fma_f32 v14, v248, v10, -v12
	v_fma_f32 v15, v249, v10, v13
	v_add_f32_e32 v10, v14, v16
	v_add_f32_e32 v11, v15, v17
	v_cvt_pk_bf16_f32 v76, v10, v11
	ds_write_b32 v32, v76 offset:768
	ds_read_b128 v[72:75], v33
	v_lshlrev_b32_e32 v16, 16, v48
	v_lshlrev_b32_e32 v17, 16, v52
	v_mul_f32_e32 v12, v249, v11
	v_mul_f32_e32 v13, v248, v11
	v_fma_f32 v14, v248, v10, -v12
	v_fma_f32 v15, v249, v10, v13
	v_add_f32_e32 v10, v14, v16
	v_add_f32_e32 v11, v15, v17
	s_waitcnt lgkmcnt(0)
; #define GAS __attribute__((address_space(1)))
; #define LAS __attribute__((address_space(3)))
; #define VM_WAIT() asm volatile("s_waitcnt vmcnt(0)" ::: "memory")
; __device__ __forceinline__ unsigned xb_add(unsigned* p, unsigned v) { return __hip_atomic_fetch_add(p, v, __ATOMIC_RELAXED, __HIP_MEMORY_SCOPE_AGENT); }
; __device__ __forceinline__ void scan_pair(Frame& F, const int g, const int b, unsigned long long& pt0, unsigned long long& pt1) {
;     ...
;         } else {
; #pragma unroll
;             for (int i = 0; i < 64; ++i) { const int e = 7 - (i & 7);
;                 ((LAS unsigned*)tile)[(i & 3) * 64 + n] = pk2(hr, hi);
;                 if ((i & 3) == 3) { const u32x4 w = *(const LAS u32x4*)((const LAS char*)tile + n * 16); *(GAS u32x4*)hp = w; hp += hstep4; asm volatile("" : "+v"(hp)); }
;                 cmul_acc(hr, hi, aTr, aTi, bf2f(pre[i >> 3][e >> 1] >> (16 * (e & 1))), bf2f(pim[i >> 3][e >> 1] >> (16 * (e & 1)))); }
;         }
;         asm volatile("" ::: "memory"); }
; __global__ void __launch_bounds__(512, 2) mk_fwd(Args args) {
;     ...
;             if (PROBE_SSM_PART >= 0) VM_WAIT();
;             __syncthreads();
;             if (PROBE_SSM_PART == 1) pt1 = __builtin_amdgcn_s_memrealtime(); if (PROBE_SSM_PART == 2) pt0 = __builtin_amdgcn_s_memrealtime();
;             if (F.tid == 0) (void)xb_add((unsigned*)(ws + WS_CTL) + CW_PAIR + g, 1u);
	global_store_dwordx4 v31, v[72:75], s[28:29]
	s_sub_u32 s28, s28, 0x200
	s_subb_u32 s29, s29, 0
	global_load_dwordx4 v[48:51], v30, s[10:11]
	global_load_dwordx4 v[52:55], v30, s[10:11] offset:1024
	s_sub_u32 s10, s10, 0x1000
	s_subb_u32 s11, s11, 0
	s_waitcnt vmcnt(12)
	v_cvt_pk_bf16_f32 v76, v10, v11
	ds_write_b32 v32, v76
	v_and_b32_e32 v16, 0xffff0000, v59
	v_and_b32_e32 v17, 0xffff0000, v63
	v_mul_f32_e32 v12, v249, v11
	v_mul_f32_e32 v13, v248, v11
	v_fma_f32 v14, v248, v10, -v12
	v_fma_f32 v15, v249, v10, v13
	v_add_f32_e32 v10, v14, v16
	v_add_f32_e32 v11, v15, v17
	v_cvt_pk_bf16_f32 v76, v10, v11
	ds_write_b32 v32, v76 offset:256
	v_lshlrev_b32_e32 v16, 16, v59
	v_lshlrev_b32_e32 v17, 16, v63
	v_mul_f32_e32 v12, v249, v11
	v_mul_f32_e32 v13, v248, v11
	v_fma_f32 v14, v248, v10, -v12
	v_fma_f32 v15, v249, v10, v13
	v_add_f32_e32 v10, v14, v16
	v_add_f32_e32 v11, v15, v17
	v_cvt_pk_bf16_f32 v76, v10, v11
	ds_write_b32 v32, v76 offset:512
	v_and_b32_e32 v16, 0xffff0000, v58
	v_and_b32_e32 v17, 0xffff0000, v62
	v_mul_f32_e32 v12, v249, v11
	v_mul_f32_e32 v13, v248, v11
	v_fma_f32 v14, v248, v10, -v12
	v_fma_f32 v15, v249, v10, v13
	v_add_f32_e32 v10, v14, v16
	v_add_f32_e32 v11, v15, v17
	v_cvt_pk_bf16_f32 v76, v10, v11
	ds_write_b32 v32, v76 offset:768
	ds_read_b128 v[72:75], v33
	v_lshlrev_b32_e32 v16, 16, v58
	v_lshlrev_b32_e32 v17, 16, v62
	v_mul_f32_e32 v12, v249, v11
	v_mul_f32_e32 v13, v248, v11
	v_fma_f32 v14, v248, v10, -v12
	v_fma_f32 v15, v249, v10, v13
	v_add_f32_e32 v10, v14, v16
	v_add_f32_e32 v11, v15, v17
	s_waitcnt lgkmcnt(0)
	global_store_dwordx4 v31, v[72:75], s[28:29]
	s_sub_u32 s28, s28, 0x200
	s_subb_u32 s29, s29, 0
	v_cvt_pk_bf16_f32 v76, v10, v11
	ds_write_b32 v32, v76
	v_and_b32_e32 v16, 0xffff0000, v57
	v_and_b32_e32 v17, 0xffff0000, v61
	v_mul_f32_e32 v12, v249, v11
	v_mul_f32_e32 v13, v248, v11
	v_fma_f32 v14, v248, v10, -v12
	v_fma_f32 v15, v249, v10, v13
	v_add_f32_e32 v10, v14, v16
	v_add_f32_e32 v11, v15, v17
	v_cvt_pk_bf16_f32 v76, v10, v11
	ds_write_b32 v32, v76 offset:256
	v_lshlrev_b32_e32 v16, 16, v57
	v_lshlrev_b32_e32 v17, 16, v61
	v_mul_f32_e32 v12, v249, v11
	v_mul_f32_e32 v13, v248, v11
	v_fma_f32 v14, v248, v10, -v12
	v_fma_f32 v15, v249, v10, v13
	v_add_f32_e32 v10, v14, v16
	v_add_f32_e32 v11, v15, v17
	v_cvt_pk_bf16_f32 v76, v10, v11
	ds_write_b32 v32, v76 offset:512
	v_and_b32_e32 v16, 0xffff0000, v56
	v_and_b32_e32 v17, 0xffff0000, v60
	v_mul_f32_e32 v12, v249, v11
	v_mul_f32_e32 v13, v248, v11
	v_fma_f32 v14, v248, v10, -v12
	v_fma_f32 v15, v249, v10, v13
	v_add_f32_e32 v10, v14, v16
	v_add_f32_e32 v11, v15, v17
	v_cvt_pk_bf16_f32 v76, v10, v11
	ds_write_b32 v32, v76 offset:768
	ds_read_b128 v[72:75], v33
	v_lshlrev_b32_e32 v16, 16, v56
	v_lshlrev_b32_e32 v17, 16, v60
	v_mul_f32_e32 v12, v249, v11
	v_mul_f32_e32 v13, v248, v11
	v_fma_f32 v14, v248, v10, -v12
	v_fma_f32 v15, v249, v10, v13
	v_add_f32_e32 v10, v14, v16
	v_add_f32_e32 v11, v15, v17
	s_waitcnt lgkmcnt(0)
	global_store_dwordx4 v31, v[72:75], s[28:29]
	s_sub_u32 s28, s28, 0x200
	s_subb_u32 s29, s29, 0
	global_load_dwordx4 v[56:59], v30, s[10:11]
	global_load_dwordx4 v[60:63], v30, s[10:11] offset:1024
	s_sub_u32 s10, s10, 0x1000
	s_subb_u32 s11, s11, 0
	s_waitcnt vmcnt(12)
	v_cvt_pk_bf16_f32 v76, v10, v11
	ds_write_b32 v32, v76
	v_and_b32_e32 v16, 0xffff0000, v67
	v_and_b32_e32 v17, 0xffff0000, v71
	v_mul_f32_e32 v12, v249, v11
	v_mul_f32_e32 v13, v248, v11
	v_fma_f32 v14, v248, v10, -v12
	v_fma_f32 v15, v249, v10, v13
	v_add_f32_e32 v10, v14, v16
	v_add_f32_e32 v11, v15, v17
	v_cvt_pk_bf16_f32 v76, v10, v11
	ds_write_b32 v32, v76 offset:256
	v_lshlrev_b32_e32 v16, 16, v67
	v_lshlrev_b32_e32 v17, 16, v71
	v_mul_f32_e32 v12, v249, v11
	v_mul_f32_e32 v13, v248, v11
	v_fma_f32 v14, v248, v10, -v12
	v_fma_f32 v15, v249, v10, v13
	v_add_f32_e32 v10, v14, v16
	v_add_f32_e32 v11, v15, v17
	v_cvt_pk_bf16_f32 v76, v10, v11
	ds_write_b32 v32, v76 offset:512
	v_and_b32_e32 v16, 0xffff0000, v66
	v_and_b32_e32 v17, 0xffff0000, v70
	v_mul_f32_e32 v12, v249, v11
	v_mul_f32_e32 v13, v248, v11
	v_fma_f32 v14, v248, v10, -v12
	v_fma_f32 v15, v249, v10, v13
	v_add_f32_e32 v10, v14, v16
	v_add_f32_e32 v11, v15, v17
	v_cvt_pk_bf16_f32 v76, v10, v11
	ds_write_b32 v32, v76 offset:768
	ds_read_b128 v[72:75], v33
	v_lshlrev_b32_e32 v16, 16, v66
	v_lshlrev_b32_e32 v17, 16, v70
	v_mul_f32_e32 v12, v249, v11
	v_mul_f32_e32 v13, v248, v11
	v_fma_f32 v14, v248, v10, -v12
	v_fma_f32 v15, v249, v10, v13
	v_add_f32_e32 v10, v14, v16
	v_add_f32_e32 v11, v15, v17
	s_waitcnt lgkmcnt(0)
	global_store_dwordx4 v31, v[72:75], s[28:29]
	s_sub_u32 s28, s28, 0x200
	s_subb_u32 s29, s29, 0
	v_cvt_pk_bf16_f32 v76, v10, v11
	ds_write_b32 v32, v76
	v_and_b32_e32 v16, 0xffff0000, v65
	v_and_b32_e32 v17, 0xffff0000, v69
	v_mul_f32_e32 v12, v249, v11
	v_mul_f32_e32 v13, v248, v11
	v_fma_f32 v14, v248, v10, -v12
	v_fma_f32 v15, v249, v10, v13
	v_add_f32_e32 v10, v14, v16
	v_add_f32_e32 v11, v15, v17
	v_cvt_pk_bf16_f32 v76, v10, v11
	ds_write_b32 v32, v76 offset:256
	v_lshlrev_b32_e32 v16, 16, v65
	v_lshlrev_b32_e32 v17, 16, v69
	v_mul_f32_e32 v12, v249, v11
	v_mul_f32_e32 v13, v248, v11
	v_fma_f32 v14, v248, v10, -v12
	v_fma_f32 v15, v249, v10, v13
	v_add_f32_e32 v10, v14, v16
	v_add_f32_e32 v11, v15, v17
	v_cvt_pk_bf16_f32 v76, v10, v11
	ds_write_b32 v32, v76 offset:512
	v_and_b32_e32 v16, 0xffff0000, v64
	v_and_b32_e32 v17, 0xffff0000, v68
	v_mul_f32_e32 v12, v249, v11
	v_mul_f32_e32 v13, v248, v11
	v_fma_f32 v14, v248, v10, -v12
	v_fma_f32 v15, v249, v10, v13
	v_add_f32_e32 v10, v14, v16
	v_add_f32_e32 v11, v15, v17
	v_cvt_pk_bf16_f32 v76, v10, v11
	ds_write_b32 v32, v76 offset:768
	ds_read_b128 v[72:75], v33
	v_lshlrev_b32_e32 v16, 16, v64
	v_lshlrev_b32_e32 v17, 16, v68
	v_mul_f32_e32 v12, v249, v11
	v_mul_f32_e32 v13, v248, v11
	v_fma_f32 v14, v248, v10, -v12
	v_fma_f32 v15, v249, v10, v13
	v_add_f32_e32 v10, v14, v16
	v_add_f32_e32 v11, v15, v17
	s_waitcnt lgkmcnt(0)
	global_store_dwordx4 v31, v[72:75], s[28:29]
	s_sub_u32 s28, s28, 0x200
	s_subb_u32 s29, s29, 0
	global_load_dwordx4 v[64:67], v30, s[10:11]
	global_load_dwordx4 v[68:71], v30, s[10:11] offset:1024
	s_sub_u32 s10, s10, 0x1000
	s_subb_u32 s11, s11, 0
	s_sub_i32 s16, s16, 1
	s_cmp_lg_u32 s16, 0
	s_cbranch_scc1 .Lscl_p2r1
	s_waitcnt vmcnt(0)
.Lsc_end:
.LBB0_574:
	s_waitcnt lgkmcnt(0)
	s_barrier
	s_mov_b64 s[4:5], exec
	v_readlane_b32 s6, v253, 5
	v_readlane_b32 s7, v253, 6
	s_and_b64 s[6:7], s[4:5], s[6:7]
	s_mov_b64 exec, s[6:7]
	s_cbranch_execz .LBB0_577
	s_mov_b64 s[6:7], exec
	v_mbcnt_lo_u32_b32 v2, s6, 0
	v_mbcnt_hi_u32_b32 v2, s7, v2
	v_cmp_eq_u32_e32 vcc, 0, v2
	s_and_b64 s[10:11], exec, vcc
	s_mov_b64 exec, s[10:11]
	s_cbranch_execz .LBB0_577
	s_lshl_b64 s[10:11], s[60:61], 2
	v_readlane_b32 s2, v253, 51
	s_add_u32 s10, s2, s10
	v_readlane_b32 s2, v253, 52
	s_addc_u32 s11, s2, s11
	s_bcnt1_i32_b64 s2, s[6:7]
	v_mov_b32_e32 v2, s2
	global_atomic_add v131, v2, s[10:11]
